# all load segments issue their LDS reads first, loop-control SALU in the MFMA tail, barrier one MFMA early
# baseline (speedup 1.0000x reference)
; #define PG8_STAGE(bufoff, gbase, voff) do { _Pragma("unroll") for (int _i = 0; _i < 2; ++_i) \
;         __builtin_amdgcn_global_load_lds((const unsigned*)((const char*)(gbase) + (voff)[_i]), (LAS unsigned*)(lds + (bufoff) + ldsw + _i * 8192), 16, 0, 0); } while (0)
; #define PG8_LDA(dst, b, h) do { _Pragma("unroll") for (int m = 0; m < 4; ++m) _Pragma("unroll") for (int k = 0; k < 2; ++k) dst[m][k] = *(const LAS bf16x8*)(lds + PG8_SA(b, h) + aoff + m * 2048 + k * 1024); } while (0)
; #define PG8_LDB(dst, b, h) do { _Pragma("unroll") for (int n = 0; n < 2; ++n) _Pragma("unroll") for (int k = 0; k < 2; ++k) dst[n][k] = *(const LAS bf16x8*)(lds + PG8_SB(b, h) + boff + n * 2048 + k * 1024); } while (0)
; #define PG8_MMA(ai, bj, At, Bt) do { __builtin_amdgcn_s_setprio(1); _Pragma("unroll") for (int m = 0; m < 4; ++m) _Pragma("unroll") for (int n = 0; n < 2; ++n) _Pragma("unroll") for (int k = 0; k < 2; ++k) \
;         acc[ai][bj][m][n] = __builtin_amdgcn_mfma_f32_16x16x32_bf16(Bt[n][k], At[m][k], acc[ai][bj][m][n], 0, 0, 0); __builtin_amdgcn_s_setprio(0); } while (0)
; #define PG8_WAIT_V(n) asm volatile("s_waitcnt vmcnt(" #n ")" ::: "memory")
; #define PG8_WAIT_L(n) asm volatile("s_waitcnt lgkmcnt(" #n ")" ::: "memory")
; #define PG8_BAR __builtin_amdgcn_s_barrier()
; #define PG8_SCHED __builtin_amdgcn_sched_barrier(0)
; template <class Epi, bool KREV = false>
; __device__ __forceinline__ void gemm_phase(LAS unsigned char* lds, const Gemm g, const StaticOrder& S, const Epi& E, int wave_s) {
;     ...
;             PG8_LDB(B0, 0, 0); PG8_LDB(B1, 0, 1); PG8_SCHED; PG8_LDA(At, 0, 0); PG8_STAGE(PG8_SA(1, 1), a1 + hstep, voffA);
;             PG8_WAIT_V(8); PG8_WAIT_L(0); PG8_BAR; PG8_MMA(0, 0, At, B0); PG8_MMA(0, 1, At, B1); PG8_BAR; PG8_SCHED;
;             PG8_LDA(At, 0, 1); PG8_STAGE(PG8_SB(0, 0), b2, voffB); PG8_STAGE(PG8_SB(0, 1), b2 + bh, voffB); PG8_STAGE(PG8_SA(0, 0), a2, voffA);
;             PG8_WAIT_V(8); PG8_WAIT_L(0); PG8_BAR; PG8_MMA(1, 0, At, B0); PG8_MMA(1, 1, At, B1); PG8_BAR; PG8_SCHED;
.LBB0_162:
	v_add_u32_e32 v138, 0x10000, v140
	ds_read_b128 v[146:149], v138
	ds_read_b128 v[150:153], v138 offset:1024
	ds_read_b128 v[154:157], v138 offset:2048
	ds_read_b128 v[158:161], v138 offset:3072
	v_add_u32_e32 v138, 0x14000, v140
	ds_read_b128 v[162:165], v138
	ds_read_b128 v[166:169], v138 offset:1024
	ds_read_b128 v[170:173], v138 offset:2048
	ds_read_b128 v[178:181], v138 offset:3072
	ds_read_b128 v[182:185], v143
	ds_read_b128 v[186:189], v143 offset:1024
	ds_read_b128 v[190:193], v143 offset:2048
	ds_read_b128 v[194:197], v143 offset:3072
	ds_read_b128 v[198:201], v143 offset:4096
	ds_read_b128 v[202:205], v143 offset:5120
	ds_read_b128 v[218:221], v143 offset:6144
	ds_read_b128 v[222:225], v143 offset:7168
	s_add_u32 s24, s22, 0xfff80080
	s_addc_u32 s25, s23, -1
	s_add_i32 s50, 0, 0x10000
	s_cmp_eq_u32 s49, 28
	s_cselect_b32 s27, s43, s25
	s_cselect_b32 s26, s44, s24
	s_cselect_b32 s25, s45, s48
	s_cselect_b32 s24, s46, s47
	s_add_i32 s52, 0, 0x14000
	s_add_i32 m0, s9, 0xc000
	s_nop 0
	global_load_lds_dwordx4 v134, s[22:23]
	s_add_i32 m0, s9, 0xe000
	s_nop 0
	global_load_lds_dwordx4 v136, s[22:23]
	s_waitcnt vmcnt(8)
	s_waitcnt lgkmcnt(0)
	s_barrier
	s_setprio 1
	s_waitcnt lgkmcnt(0)
	v_mfma_f32_16x16x32_bf16 v[124:127], v[146:149], v[182:185], v[124:127]
	v_mfma_f32_16x16x32_bf16 v[120:123], v[154:157], v[182:185], v[120:123]
	v_mfma_f32_16x16x32_bf16 v[108:111], v[146:149], v[190:193], v[108:111]
	v_mfma_f32_16x16x32_bf16 v[104:107], v[154:157], v[190:193], v[104:107]
	v_mfma_f32_16x16x32_bf16 v[92:95], v[146:149], v[198:201], v[92:95]
	v_mfma_f32_16x16x32_bf16 v[88:91], v[154:157], v[198:201], v[88:91]
	v_mfma_f32_16x16x32_bf16 v[76:79], v[146:149], v[218:221], v[76:79]
	v_mfma_f32_16x16x32_bf16 v[72:75], v[154:157], v[218:221], v[72:75]
	v_mfma_f32_16x16x32_bf16 v[124:127], v[150:153], v[186:189], v[124:127]
	v_mfma_f32_16x16x32_bf16 v[120:123], v[158:161], v[186:189], v[120:123]
	v_mfma_f32_16x16x32_bf16 v[108:111], v[150:153], v[194:197], v[108:111]
	v_mfma_f32_16x16x32_bf16 v[104:107], v[158:161], v[194:197], v[104:107]
	v_mfma_f32_16x16x32_bf16 v[92:95], v[150:153], v[202:205], v[92:95]
	v_mfma_f32_16x16x32_bf16 v[88:91], v[158:161], v[202:205], v[88:91]
	v_mfma_f32_16x16x32_bf16 v[76:79], v[150:153], v[222:225], v[76:79]
	v_mfma_f32_16x16x32_bf16 v[72:75], v[158:161], v[222:225], v[72:75]
	s_setprio 0
	s_setprio 1
	v_mfma_f32_16x16x32_bf16 v[116:119], v[162:165], v[182:185], v[116:119]
	v_mfma_f32_16x16x32_bf16 v[112:115], v[170:173], v[182:185], v[112:115]
	v_mfma_f32_16x16x32_bf16 v[100:103], v[162:165], v[190:193], v[100:103]
	v_mfma_f32_16x16x32_bf16 v[96:99], v[170:173], v[190:193], v[96:99]
	v_mfma_f32_16x16x32_bf16 v[84:87], v[162:165], v[198:201], v[84:87]
	v_mfma_f32_16x16x32_bf16 v[80:83], v[170:173], v[198:201], v[80:83]
	v_mfma_f32_16x16x32_bf16 v[68:71], v[162:165], v[218:221], v[68:71]
	v_mfma_f32_16x16x32_bf16 v[64:67], v[170:173], v[218:221], v[64:67]
	v_mfma_f32_16x16x32_bf16 v[116:119], v[166:169], v[186:189], v[116:119]
	v_mfma_f32_16x16x32_bf16 v[112:115], v[178:181], v[186:189], v[112:115]
	v_mfma_f32_16x16x32_bf16 v[100:103], v[166:169], v[194:197], v[100:103]
	v_mfma_f32_16x16x32_bf16 v[96:99], v[178:181], v[194:197], v[96:99]
	v_mfma_f32_16x16x32_bf16 v[84:87], v[166:169], v[202:205], v[84:87]
	v_mfma_f32_16x16x32_bf16 v[80:83], v[178:181], v[202:205], v[80:83]
	v_mfma_f32_16x16x32_bf16 v[68:71], v[166:169], v[222:225], v[68:71]
	s_barrier
	v_mfma_f32_16x16x32_bf16 v[64:67], v[178:181], v[222:225], v[64:67]
	s_setprio 0
	ds_read_b128 v[182:185], v143 offset:16384
	ds_read_b128 v[186:189], v143 offset:17408
	ds_read_b128 v[190:193], v143 offset:18432
	ds_read_b128 v[194:197], v143 offset:19456
	ds_read_b128 v[198:201], v143 offset:20480
	ds_read_b128 v[202:205], v143 offset:21504
	ds_read_b128 v[218:221], v143 offset:22528
	ds_read_b128 v[222:225], v143 offset:23552
	s_add_u32 s98, s24, s2
	s_addc_u32 s99, s25, s3
	s_add_u32 s100, s26, s2
	s_addc_u32 s101, s27, s3
	s_add_i32 s50, s50, s29
	s_mov_b32 m0, s50
	s_nop 0
	global_load_lds_dwordx4 v176, s[24:25]
	s_add_i32 m0, s50, 0x2000
	s_add_u32 s50, s24, 0x80000
	s_addc_u32 s51, s25, 0
	s_add_i32 s52, s52, s29
	global_load_lds_dwordx4 v132, s[24:25]
	s_mov_b32 m0, s52
	v_lshl_add_u64 v[226:227], s[26:27], 0, v[130:131]
	global_load_lds_dwordx4 v176, s[50:51]
	s_add_i32 m0, s52, 0x2000
	s_nop 0
	global_load_lds_dwordx4 v132, s[50:51]
	s_mov_b32 m0, s9
	s_nop 0
	global_load_lds_dwordx4 v128, s[26:27]
	s_mov_b32 m0, s11
	s_nop 0
	global_load_lds_dwordx4 v130, s[26:27]
	s_waitcnt vmcnt(8)
	s_waitcnt lgkmcnt(0)
	s_barrier
; #define PG8_STAGE(bufoff, gbase, voff) do { _Pragma("unroll") for (int _i = 0; _i < 2; ++_i) \
;         __builtin_amdgcn_global_load_lds((const unsigned*)((const char*)(gbase) + (voff)[_i]), (LAS unsigned*)(lds + (bufoff) + ldsw + _i * 8192), 16, 0, 0); } while (0)
; #define PG8_LDA(dst, b, h) do { _Pragma("unroll") for (int m = 0; m < 4; ++m) _Pragma("unroll") for (int k = 0; k < 2; ++k) dst[m][k] = *(const LAS bf16x8*)(lds + PG8_SA(b, h) + aoff + m * 2048 + k * 1024); } while (0)
; #define PG8_LDB(dst, b, h) do { _Pragma("unroll") for (int n = 0; n < 2; ++n) _Pragma("unroll") for (int k = 0; k < 2; ++k) dst[n][k] = *(const LAS bf16x8*)(lds + PG8_SB(b, h) + boff + n * 2048 + k * 1024); } while (0)
; #define PG8_MMA(ai, bj, At, Bt) do { __builtin_amdgcn_s_setprio(1); _Pragma("unroll") for (int m = 0; m < 4; ++m) _Pragma("unroll") for (int n = 0; n < 2; ++n) _Pragma("unroll") for (int k = 0; k < 2; ++k) \
;         acc[ai][bj][m][n] = __builtin_amdgcn_mfma_f32_16x16x32_bf16(Bt[n][k], At[m][k], acc[ai][bj][m][n], 0, 0, 0); __builtin_amdgcn_s_setprio(0); } while (0)
; #define PG8_WAIT_V(n) asm volatile("s_waitcnt vmcnt(" #n ")" ::: "memory")
; #define PG8_WAIT_L(n) asm volatile("s_waitcnt lgkmcnt(" #n ")" ::: "memory")
; #define PG8_BAR __builtin_amdgcn_s_barrier()
; #define PG8_SCHED __builtin_amdgcn_sched_barrier(0)
; template <class Epi, bool KREV = false>
; __device__ __forceinline__ void gemm_phase(LAS unsigned char* lds, const Gemm g, const StaticOrder& S, const Epi& E, int wave_s) {
;     ...
;             PG8_WAIT_V(8); PG8_WAIT_L(0); PG8_BAR; PG8_MMA(1, 0, At, B0); PG8_MMA(1, 1, At, B1); PG8_BAR; PG8_SCHED;
;             PG8_LDB(B0, 1, 0); PG8_LDB(B1, 1, 1); PG8_SCHED; PG8_LDA(At, 1, 0); PG8_STAGE(PG8_SA(0, 1), a2 + hstep, voffA);
;             PG8_WAIT_V(8); PG8_WAIT_L(0); PG8_BAR; PG8_MMA(0, 0, At, B0); PG8_MMA(0, 1, At, B1); PG8_BAR; PG8_SCHED;
	s_setprio 1
	s_waitcnt lgkmcnt(0)
	v_mfma_f32_16x16x32_bf16 v[60:63], v[146:149], v[182:185], v[60:63]
	v_mfma_f32_16x16x32_bf16 v[56:59], v[154:157], v[182:185], v[56:59]
	v_mfma_f32_16x16x32_bf16 v[44:47], v[146:149], v[190:193], v[44:47]
	v_mfma_f32_16x16x32_bf16 v[40:43], v[154:157], v[190:193], v[40:43]
	v_mfma_f32_16x16x32_bf16 v[28:31], v[146:149], v[198:201], v[28:31]
	v_mfma_f32_16x16x32_bf16 v[24:27], v[154:157], v[198:201], v[24:27]
	v_mfma_f32_16x16x32_bf16 v[12:15], v[146:149], v[218:221], v[12:15]
	v_mfma_f32_16x16x32_bf16 v[8:11], v[154:157], v[218:221], v[8:11]
	v_mfma_f32_16x16x32_bf16 v[60:63], v[150:153], v[186:189], v[60:63]
	v_mfma_f32_16x16x32_bf16 v[56:59], v[158:161], v[186:189], v[56:59]
	v_mfma_f32_16x16x32_bf16 v[44:47], v[150:153], v[194:197], v[44:47]
	v_mfma_f32_16x16x32_bf16 v[40:43], v[158:161], v[194:197], v[40:43]
	v_mfma_f32_16x16x32_bf16 v[28:31], v[150:153], v[202:205], v[28:31]
	v_mfma_f32_16x16x32_bf16 v[24:27], v[158:161], v[202:205], v[24:27]
	v_mfma_f32_16x16x32_bf16 v[12:15], v[150:153], v[222:225], v[12:15]
	v_mfma_f32_16x16x32_bf16 v[8:11], v[158:161], v[222:225], v[8:11]
	s_setprio 0
	s_setprio 1
	v_mfma_f32_16x16x32_bf16 v[52:55], v[162:165], v[182:185], v[52:55]
	v_mfma_f32_16x16x32_bf16 v[48:51], v[170:173], v[182:185], v[48:51]
	v_mfma_f32_16x16x32_bf16 v[36:39], v[162:165], v[190:193], v[36:39]
	v_mfma_f32_16x16x32_bf16 v[32:35], v[170:173], v[190:193], v[32:35]
	v_mfma_f32_16x16x32_bf16 v[20:23], v[162:165], v[198:201], v[20:23]
	v_mfma_f32_16x16x32_bf16 v[16:19], v[170:173], v[198:201], v[16:19]
	v_mfma_f32_16x16x32_bf16 v[4:7], v[162:165], v[218:221], v[4:7]
	v_mfma_f32_16x16x32_bf16 v[0:3], v[170:173], v[218:221], v[0:3]
	v_mfma_f32_16x16x32_bf16 v[52:55], v[166:169], v[186:189], v[52:55]
	v_mfma_f32_16x16x32_bf16 v[48:51], v[178:181], v[186:189], v[48:51]
	v_mfma_f32_16x16x32_bf16 v[36:39], v[166:169], v[194:197], v[36:39]
	v_mfma_f32_16x16x32_bf16 v[32:35], v[178:181], v[194:197], v[32:35]
	v_mfma_f32_16x16x32_bf16 v[20:23], v[166:169], v[202:205], v[20:23]
	v_mfma_f32_16x16x32_bf16 v[16:19], v[178:181], v[202:205], v[16:19]
	v_mfma_f32_16x16x32_bf16 v[4:7], v[166:169], v[222:225], v[4:7]
	s_barrier
	v_mfma_f32_16x16x32_bf16 v[0:3], v[178:181], v[222:225], v[0:3]
	s_setprio 0
	v_add_u32_e32 v145, 0x18000, v140
	ds_read_b128 v[146:149], v145
	ds_read_b128 v[150:153], v145 offset:1024
	ds_read_b128 v[154:157], v145 offset:2048
	ds_read_b128 v[158:161], v145 offset:3072
	v_add_u32_e32 v145, 0x1c000, v140
	ds_read_b128 v[162:165], v145
	ds_read_b128 v[166:169], v145 offset:1024
	ds_read_b128 v[170:173], v145 offset:2048
	ds_read_b128 v[178:181], v145 offset:3072
	ds_read_b128 v[182:185], v143 offset:32768
	ds_read_b128 v[186:189], v143 offset:33792
	ds_read_b128 v[190:193], v143 offset:34816
	ds_read_b128 v[194:197], v143 offset:35840
	ds_read_b128 v[198:201], v143 offset:36864
	ds_read_b128 v[202:205], v143 offset:37888
	ds_read_b128 v[218:221], v143 offset:38912
	ds_read_b128 v[222:225], v143 offset:39936
	s_add_i32 s50, 0, 0x18000
	s_add_i32 s51, 0, 0x1c000
	s_add_u32 s26, s26, 0x80000
	s_addc_u32 s27, s27, 0
	s_mov_b32 m0, s36
	s_nop 0
	global_load_lds_dwordx4 v128, s[26:27]
	s_mov_b32 m0, s37
	s_nop 0
	global_load_lds_dwordx4 v130, s[26:27]
	s_waitcnt vmcnt(8)
	s_waitcnt lgkmcnt(0)
	s_barrier
	s_setprio 1
	s_waitcnt lgkmcnt(0)
	v_mfma_f32_16x16x32_bf16 v[124:127], v[146:149], v[182:185], v[124:127]
	v_mfma_f32_16x16x32_bf16 v[120:123], v[154:157], v[182:185], v[120:123]
	v_mfma_f32_16x16x32_bf16 v[108:111], v[146:149], v[190:193], v[108:111]
	v_mfma_f32_16x16x32_bf16 v[104:107], v[154:157], v[190:193], v[104:107]
	v_mfma_f32_16x16x32_bf16 v[92:95], v[146:149], v[198:201], v[92:95]
	v_mfma_f32_16x16x32_bf16 v[88:91], v[154:157], v[198:201], v[88:91]
	v_mfma_f32_16x16x32_bf16 v[76:79], v[146:149], v[218:221], v[76:79]
	v_mfma_f32_16x16x32_bf16 v[72:75], v[154:157], v[218:221], v[72:75]
	v_mfma_f32_16x16x32_bf16 v[124:127], v[150:153], v[186:189], v[124:127]
	v_mfma_f32_16x16x32_bf16 v[120:123], v[158:161], v[186:189], v[120:123]
	v_mfma_f32_16x16x32_bf16 v[108:111], v[150:153], v[194:197], v[108:111]
	v_mfma_f32_16x16x32_bf16 v[104:107], v[158:161], v[194:197], v[104:107]
	v_mfma_f32_16x16x32_bf16 v[92:95], v[150:153], v[202:205], v[92:95]
	v_mfma_f32_16x16x32_bf16 v[88:91], v[158:161], v[202:205], v[88:91]
	v_mfma_f32_16x16x32_bf16 v[76:79], v[150:153], v[222:225], v[76:79]
	v_mfma_f32_16x16x32_bf16 v[72:75], v[158:161], v[222:225], v[72:75]
	s_setprio 0
	s_setprio 1
	v_mfma_f32_16x16x32_bf16 v[116:119], v[162:165], v[182:185], v[116:119]
	v_mfma_f32_16x16x32_bf16 v[112:115], v[170:173], v[182:185], v[112:115]
	v_mfma_f32_16x16x32_bf16 v[100:103], v[162:165], v[190:193], v[100:103]
	v_mfma_f32_16x16x32_bf16 v[96:99], v[170:173], v[190:193], v[96:99]
	v_mfma_f32_16x16x32_bf16 v[84:87], v[162:165], v[198:201], v[84:87]
	v_mfma_f32_16x16x32_bf16 v[80:83], v[170:173], v[198:201], v[80:83]
	v_mfma_f32_16x16x32_bf16 v[68:71], v[162:165], v[218:221], v[68:71]
	v_mfma_f32_16x16x32_bf16 v[64:67], v[170:173], v[218:221], v[64:67]
	v_mfma_f32_16x16x32_bf16 v[116:119], v[166:169], v[186:189], v[116:119]
	v_mfma_f32_16x16x32_bf16 v[112:115], v[178:181], v[186:189], v[112:115]
	v_mfma_f32_16x16x32_bf16 v[100:103], v[166:169], v[194:197], v[100:103]
	v_mfma_f32_16x16x32_bf16 v[96:99], v[178:181], v[194:197], v[96:99]
	v_mfma_f32_16x16x32_bf16 v[84:87], v[166:169], v[202:205], v[84:87]
	v_mfma_f32_16x16x32_bf16 v[80:83], v[178:181], v[202:205], v[80:83]
	v_mfma_f32_16x16x32_bf16 v[68:71], v[166:169], v[222:225], v[68:71]
	s_barrier
; #define PG8_STAGE(bufoff, gbase, voff) do { _Pragma("unroll") for (int _i = 0; _i < 2; ++_i) \
;         __builtin_amdgcn_global_load_lds((const unsigned*)((const char*)(gbase) + (voff)[_i]), (LAS unsigned*)(lds + (bufoff) + ldsw + _i * 8192), 16, 0, 0); } while (0)
; #define PG8_LDA(dst, b, h) do { _Pragma("unroll") for (int m = 0; m < 4; ++m) _Pragma("unroll") for (int k = 0; k < 2; ++k) dst[m][k] = *(const LAS bf16x8*)(lds + PG8_SA(b, h) + aoff + m * 2048 + k * 1024); } while (0)
; #define PG8_MMA(ai, bj, At, Bt) do { __builtin_amdgcn_s_setprio(1); _Pragma("unroll") for (int m = 0; m < 4; ++m) _Pragma("unroll") for (int n = 0; n < 2; ++n) _Pragma("unroll") for (int k = 0; k < 2; ++k) \
;         acc[ai][bj][m][n] = __builtin_amdgcn_mfma_f32_16x16x32_bf16(Bt[n][k], At[m][k], acc[ai][bj][m][n], 0, 0, 0); __builtin_amdgcn_s_setprio(0); } while (0)
; #define PG8_WAIT_V(n) asm volatile("s_waitcnt vmcnt(" #n ")" ::: "memory")
; #define PG8_WAIT_L(n) asm volatile("s_waitcnt lgkmcnt(" #n ")" ::: "memory")
; #define PG8_BAR __builtin_amdgcn_s_barrier()
; #define PG8_SCHED __builtin_amdgcn_sched_barrier(0)
; template <class Epi, bool KREV = false>
; __device__ __forceinline__ void gemm_phase(LAS unsigned char* lds, const Gemm g, const StaticOrder& S, const Epi& E, int wave_s) {
;     ...
;             PG8_LDA(At, 1, 1); PG8_STAGE(PG8_SB(1, 0), b3, voffB); PG8_STAGE(PG8_SB(1, 1), b3 + bh, voffB); PG8_STAGE(PG8_SA(1, 0), a3, voffA);
;             PG8_WAIT_V(8); PG8_WAIT_L(0); PG8_BAR; PG8_MMA(1, 0, At, B0); PG8_MMA(1, 1, At, B1); PG8_BAR; PG8_SCHED;
	v_mfma_f32_16x16x32_bf16 v[64:67], v[178:181], v[222:225], v[64:67]
	s_setprio 0
	ds_read_b128 v[182:185], v143 offset:49152
	ds_read_b128 v[186:189], v143 offset:50176
	ds_read_b128 v[190:193], v143 offset:51200
	ds_read_b128 v[194:197], v143 offset:52224
	ds_read_b128 v[198:201], v143 offset:53248
	ds_read_b128 v[202:205], v143 offset:54272
	ds_read_b128 v[218:221], v143 offset:55296
	ds_read_b128 v[222:225], v143 offset:56320
	s_add_i32 s26, s50, s29
	s_mov_b32 m0, s26
	s_nop 0
	global_load_lds_dwordx4 v176, s[98:99]
	s_add_i32 m0, s26, 0x2000
	s_add_u32 s24, s24, 0x80080
	s_addc_u32 s25, s25, 0
	s_add_i32 s26, s51, s29
	global_load_lds_dwordx4 v132, s[98:99]
	s_mov_b32 m0, s26
	s_nop 0
	global_load_lds_dwordx4 v176, s[24:25]
	s_add_i32 m0, s26, 0x2000
	s_nop 0
	global_load_lds_dwordx4 v132, s[24:25]
	s_mov_b32 m0, s38
	s_nop 0
	global_load_lds_dwordx4 v128, s[100:101]
	v_lshl_add_u64 v[138:139], v[226:227], 0, s[2:3]
	s_mov_b32 m0, s39
	s_nop 0
	global_load_lds_dwordx4 v130, s[100:101]
	s_waitcnt vmcnt(8)
	s_waitcnt lgkmcnt(0)
	s_barrier
	s_setprio 1
	s_waitcnt lgkmcnt(0)
	v_mfma_f32_16x16x32_bf16 v[60:63], v[146:149], v[182:185], v[60:63]
	v_mfma_f32_16x16x32_bf16 v[56:59], v[154:157], v[182:185], v[56:59]
	v_mfma_f32_16x16x32_bf16 v[44:47], v[146:149], v[190:193], v[44:47]
	v_mfma_f32_16x16x32_bf16 v[40:43], v[154:157], v[190:193], v[40:43]
	v_mfma_f32_16x16x32_bf16 v[28:31], v[146:149], v[198:201], v[28:31]
	v_mfma_f32_16x16x32_bf16 v[24:27], v[154:157], v[198:201], v[24:27]
	v_mfma_f32_16x16x32_bf16 v[12:15], v[146:149], v[218:221], v[12:15]
	v_mfma_f32_16x16x32_bf16 v[8:11], v[154:157], v[218:221], v[8:11]
	v_mfma_f32_16x16x32_bf16 v[60:63], v[150:153], v[186:189], v[60:63]
	v_mfma_f32_16x16x32_bf16 v[56:59], v[158:161], v[186:189], v[56:59]
	v_mfma_f32_16x16x32_bf16 v[44:47], v[150:153], v[194:197], v[44:47]
	v_mfma_f32_16x16x32_bf16 v[40:43], v[158:161], v[194:197], v[40:43]
	v_mfma_f32_16x16x32_bf16 v[28:31], v[150:153], v[202:205], v[28:31]
	v_mfma_f32_16x16x32_bf16 v[24:27], v[158:161], v[202:205], v[24:27]
	v_mfma_f32_16x16x32_bf16 v[12:15], v[150:153], v[222:225], v[12:15]
	v_mfma_f32_16x16x32_bf16 v[8:11], v[158:161], v[222:225], v[8:11]
	s_setprio 0
	s_setprio 1
	v_mfma_f32_16x16x32_bf16 v[52:55], v[162:165], v[182:185], v[52:55]
	v_mfma_f32_16x16x32_bf16 v[48:51], v[170:173], v[182:185], v[48:51]
	v_mfma_f32_16x16x32_bf16 v[36:39], v[162:165], v[190:193], v[36:39]
	v_mfma_f32_16x16x32_bf16 v[32:35], v[170:173], v[190:193], v[32:35]
	v_mfma_f32_16x16x32_bf16 v[20:23], v[162:165], v[198:201], v[20:23]
	v_mfma_f32_16x16x32_bf16 v[16:19], v[170:173], v[198:201], v[16:19]
	v_mfma_f32_16x16x32_bf16 v[4:7], v[162:165], v[218:221], v[4:7]
	v_mfma_f32_16x16x32_bf16 v[0:3], v[170:173], v[218:221], v[0:3]
	v_mfma_f32_16x16x32_bf16 v[52:55], v[166:169], v[186:189], v[52:55]
	v_mfma_f32_16x16x32_bf16 v[48:51], v[178:181], v[186:189], v[48:51]
	v_mfma_f32_16x16x32_bf16 v[36:39], v[166:169], v[194:197], v[36:39]
	v_mfma_f32_16x16x32_bf16 v[32:35], v[178:181], v[194:197], v[32:35]
	s_add_i32 s49, s49, 2
	s_add_u32 s22, s22, 0x100
	s_addc_u32 s23, s23, 0
	v_mfma_f32_16x16x32_bf16 v[20:23], v[166:169], v[202:205], v[20:23]
	s_add_u32 s47, s47, 0x100
	s_addc_u32 s48, s48, 0
	v_mfma_f32_16x16x32_bf16 v[16:19], v[178:181], v[202:205], v[16:19]
	s_cmp_gt_u32 s49, 29
	v_mfma_f32_16x16x32_bf16 v[4:7], v[166:169], v[222:225], v[4:7]
	s_barrier
	v_mfma_f32_16x16x32_bf16 v[0:3], v[178:181], v[222:225], v[0:3]
	s_setprio 0
	s_cbranch_scc0 .LBB0_162
	s_and_b64 vcc, exec, s[18:19]
	s_cbranch_vccz .LBB0_165
	s_barrier

; #define PG8_STAGE(bufoff, gbase, voff) do { _Pragma("unroll") for (int _i = 0; _i < 2; ++_i) \
;         __builtin_amdgcn_global_load_lds((const unsigned*)((const char*)(gbase) + (voff)[_i]), (LAS unsigned*)(lds + (bufoff) + ldsw + _i * 8192), 16, 0, 0); } while (0)
; #define PG8_LDA(dst, b, h) do { _Pragma("unroll") for (int m = 0; m < 4; ++m) _Pragma("unroll") for (int k = 0; k < 2; ++k) dst[m][k] = *(const LAS bf16x8*)(lds + PG8_SA(b, h) + aoff + m * 2048 + k * 1024); } while (0)
; #define PG8_LDB(dst, b, h) do { _Pragma("unroll") for (int n = 0; n < 2; ++n) _Pragma("unroll") for (int k = 0; k < 2; ++k) dst[n][k] = *(const LAS bf16x8*)(lds + PG8_SB(b, h) + boff + n * 2048 + k * 1024); } while (0)
; #define PG8_MMA(ai, bj, At, Bt) do { __builtin_amdgcn_s_setprio(1); _Pragma("unroll") for (int m = 0; m < 4; ++m) _Pragma("unroll") for (int n = 0; n < 2; ++n) _Pragma("unroll") for (int k = 0; k < 2; ++k) \
;         acc[ai][bj][m][n] = __builtin_amdgcn_mfma_f32_16x16x32_bf16(Bt[n][k], At[m][k], acc[ai][bj][m][n], 0, 0, 0); __builtin_amdgcn_s_setprio(0); } while (0)
; #define PG8_WAIT_V(n) asm volatile("s_waitcnt vmcnt(" #n ")" ::: "memory")
; #define PG8_WAIT_L(n) asm volatile("s_waitcnt lgkmcnt(" #n ")" ::: "memory")
; #define PG8_BAR __builtin_amdgcn_s_barrier()
; #define PG8_SCHED __builtin_amdgcn_sched_barrier(0)
; template <class Epi, bool KREV = false>
; __device__ __forceinline__ void gemm_phase(LAS unsigned char* lds, const Gemm g, const StaticOrder& S, const Epi& E, int wave_s) {
;     ...
;             PG8_LDB(B0, 0, 0); PG8_LDB(B1, 0, 1); PG8_SCHED; PG8_LDA(At, 0, 0); PG8_STAGE(PG8_SA(1, 1), a1 + hstep, voffA);
;             PG8_WAIT_V(8); PG8_WAIT_L(0); PG8_BAR; PG8_MMA(0, 0, At, B0); PG8_MMA(0, 1, At, B1); PG8_BAR; PG8_SCHED;
;             PG8_LDA(At, 0, 1); PG8_STAGE(PG8_SB(0, 0), b2, voffB); PG8_STAGE(PG8_SB(0, 1), b2 + bh, voffB); PG8_STAGE(PG8_SA(0, 0), a2, voffA);
;             PG8_WAIT_V(8); PG8_WAIT_L(0); PG8_BAR; PG8_MMA(1, 0, At, B0); PG8_MMA(1, 1, At, B1); PG8_BAR; PG8_SCHED;
.LBB0_640:
	s_or_b32 s80, s9, 1
	s_lshl_b64 s[46:47], s[80:81], 7
	s_sub_u32 s27, 0, s46
	s_subb_u32 s45, 0, s47
	s_add_i32 s48, 0, 0x10000
	s_add_i32 s49, 0, 0x14000
	s_add_u32 s46, s41, s27
	s_addc_u32 s47, s42, s45
	s_add_i32 m0, s34, 0xc000
	s_nop 0
	global_load_lds_dwordx4 v156, s[46:47]
	s_add_i32 m0, s34, 0xe000
	s_nop 0
	global_load_lds_dwordx4 v154, s[46:47]
	s_waitcnt vmcnt(8)
	s_waitcnt lgkmcnt(0)
	s_barrier
	s_setprio 1
	s_waitcnt lgkmcnt(0)
	v_mfma_f32_16x16x32_bf16 v[132:135], v[112:115], v[218:221], v[132:135]
	v_mfma_f32_16x16x32_bf16 v[120:123], v[136:139], v[218:221], v[120:123]
	v_mfma_f32_16x16x32_bf16 v[108:111], v[112:115], v[226:229], v[108:111]
	v_mfma_f32_16x16x32_bf16 v[104:107], v[136:139], v[226:229], v[104:107]
	v_mfma_f32_16x16x32_bf16 v[92:95], v[112:115], v[234:237], v[92:95]
	v_mfma_f32_16x16x32_bf16 v[88:91], v[136:139], v[234:237], v[88:91]
	v_mfma_f32_16x16x32_bf16 v[76:79], v[112:115], v[242:245], v[76:79]
	v_mfma_f32_16x16x32_bf16 v[72:75], v[136:139], v[242:245], v[72:75]
	v_mfma_f32_16x16x32_bf16 v[132:135], v[124:127], v[222:225], v[132:135]
	v_mfma_f32_16x16x32_bf16 v[120:123], v[140:143], v[222:225], v[120:123]
	v_mfma_f32_16x16x32_bf16 v[108:111], v[124:127], v[230:233], v[108:111]
	v_mfma_f32_16x16x32_bf16 v[104:107], v[140:143], v[230:233], v[104:107]
	v_mfma_f32_16x16x32_bf16 v[92:95], v[124:127], v[238:241], v[92:95]
	v_mfma_f32_16x16x32_bf16 v[88:91], v[140:143], v[238:241], v[88:91]
	v_mfma_f32_16x16x32_bf16 v[76:79], v[124:127], v[246:249], v[76:79]
	v_mfma_f32_16x16x32_bf16 v[72:75], v[140:143], v[246:249], v[72:75]
	s_setprio 0
	s_setprio 1
	v_mfma_f32_16x16x32_bf16 v[128:131], v[144:147], v[218:221], v[128:131]
	v_mfma_f32_16x16x32_bf16 v[116:119], v[194:197], v[218:221], v[116:119]
	v_mfma_f32_16x16x32_bf16 v[100:103], v[144:147], v[226:229], v[100:103]
	v_mfma_f32_16x16x32_bf16 v[96:99], v[194:197], v[226:229], v[96:99]
	v_mfma_f32_16x16x32_bf16 v[84:87], v[144:147], v[234:237], v[84:87]
	v_mfma_f32_16x16x32_bf16 v[80:83], v[194:197], v[234:237], v[80:83]
	v_mfma_f32_16x16x32_bf16 v[68:71], v[144:147], v[242:245], v[68:71]
	v_mfma_f32_16x16x32_bf16 v[64:67], v[194:197], v[242:245], v[64:67]
	v_mfma_f32_16x16x32_bf16 v[128:131], v[148:151], v[222:225], v[128:131]
	v_mfma_f32_16x16x32_bf16 v[116:119], v[202:205], v[222:225], v[116:119]
	v_mfma_f32_16x16x32_bf16 v[100:103], v[148:151], v[230:233], v[100:103]
	v_mfma_f32_16x16x32_bf16 v[96:99], v[202:205], v[230:233], v[96:99]
	v_mfma_f32_16x16x32_bf16 v[84:87], v[148:151], v[238:241], v[84:87]
	v_mfma_f32_16x16x32_bf16 v[80:83], v[202:205], v[238:241], v[80:83]
	v_mfma_f32_16x16x32_bf16 v[68:71], v[148:151], v[246:249], v[68:71]
	s_barrier
	v_mfma_f32_16x16x32_bf16 v[64:67], v[202:205], v[246:249], v[64:67]
	s_setprio 0
	ds_read_b128 v[218:221], v201 offset:16384
	ds_read_b128 v[222:225], v201 offset:17408
	ds_read_b128 v[226:229], v201 offset:18432
	ds_read_b128 v[230:233], v201 offset:19456
	ds_read_b128 v[234:237], v201 offset:20480
	ds_read_b128 v[238:241], v201 offset:21504
	ds_read_b128 v[242:245], v201 offset:22528
	ds_read_b128 v[246:249], v201 offset:23552
	s_add_u32 s98, s28, s78
	s_addc_u32 s99, s29, s79
	s_add_u32 s100, s30, s78
	s_addc_u32 s101, s31, s79
	s_add_i32 s27, s48, s1
	s_mov_b32 m0, s27
	s_nop 0
	global_load_lds_dwordx4 v176, s[28:29]
	s_add_i32 m0, s27, 0x2000
	s_add_u32 s46, s28, 0x80000
	s_addc_u32 s47, s29, 0
	s_add_i32 s27, s49, s1
	global_load_lds_dwordx4 v152, s[28:29]
	s_mov_b32 m0, s27
	s_nop 0
	global_load_lds_dwordx4 v176, s[46:47]
	s_add_i32 m0, s27, 0x2000
	s_nop 0
	global_load_lds_dwordx4 v152, s[46:47]
	s_mov_b32 m0, s34
	s_nop 0
	global_load_lds_dwordx4 v156, s[30:31]
	s_mov_b32 m0, s35
	s_nop 0
	global_load_lds_dwordx4 v154, s[30:31]
	s_waitcnt vmcnt(8)
	s_waitcnt lgkmcnt(0)
	s_barrier
	s_setprio 1
	s_waitcnt lgkmcnt(0)
	v_mfma_f32_16x16x32_bf16 v[60:63], v[112:115], v[218:221], v[60:63]
	v_mfma_f32_16x16x32_bf16 v[56:59], v[136:139], v[218:221], v[56:59]
	v_mfma_f32_16x16x32_bf16 v[44:47], v[112:115], v[226:229], v[44:47]
	v_mfma_f32_16x16x32_bf16 v[40:43], v[136:139], v[226:229], v[40:43]
	v_mfma_f32_16x16x32_bf16 v[28:31], v[112:115], v[234:237], v[28:31]
	v_mfma_f32_16x16x32_bf16 v[24:27], v[136:139], v[234:237], v[24:27]
	v_mfma_f32_16x16x32_bf16 v[12:15], v[112:115], v[242:245], v[12:15]
	v_mfma_f32_16x16x32_bf16 v[8:11], v[136:139], v[242:245], v[8:11]
	v_mfma_f32_16x16x32_bf16 v[60:63], v[124:127], v[222:225], v[60:63]
	v_mfma_f32_16x16x32_bf16 v[56:59], v[140:143], v[222:225], v[56:59]
	v_mfma_f32_16x16x32_bf16 v[44:47], v[124:127], v[230:233], v[44:47]
	v_mfma_f32_16x16x32_bf16 v[40:43], v[140:143], v[230:233], v[40:43]
	v_mfma_f32_16x16x32_bf16 v[28:31], v[124:127], v[238:241], v[28:31]
	v_mfma_f32_16x16x32_bf16 v[24:27], v[140:143], v[238:241], v[24:27]
	v_mfma_f32_16x16x32_bf16 v[12:15], v[124:127], v[246:249], v[12:15]
	v_mfma_f32_16x16x32_bf16 v[8:11], v[140:143], v[246:249], v[8:11]
	s_setprio 0
	s_setprio 1
	v_mfma_f32_16x16x32_bf16 v[52:55], v[144:147], v[218:221], v[52:55]
	v_mfma_f32_16x16x32_bf16 v[48:51], v[194:197], v[218:221], v[48:51]
	v_mfma_f32_16x16x32_bf16 v[36:39], v[144:147], v[226:229], v[36:39]
	v_mfma_f32_16x16x32_bf16 v[32:35], v[194:197], v[226:229], v[32:35]
	v_mfma_f32_16x16x32_bf16 v[20:23], v[144:147], v[234:237], v[20:23]
	v_mfma_f32_16x16x32_bf16 v[16:19], v[194:197], v[234:237], v[16:19]
	v_mfma_f32_16x16x32_bf16 v[4:7], v[144:147], v[242:245], v[4:7]
	v_mfma_f32_16x16x32_bf16 v[0:3], v[194:197], v[242:245], v[0:3]
	v_mfma_f32_16x16x32_bf16 v[52:55], v[148:151], v[222:225], v[52:55]
	v_mfma_f32_16x16x32_bf16 v[48:51], v[202:205], v[222:225], v[48:51]
	v_mfma_f32_16x16x32_bf16 v[36:39], v[148:151], v[230:233], v[36:39]
	v_mfma_f32_16x16x32_bf16 v[32:35], v[202:205], v[230:233], v[32:35]
	v_mfma_f32_16x16x32_bf16 v[20:23], v[148:151], v[238:241], v[20:23]
	v_mfma_f32_16x16x32_bf16 v[16:19], v[202:205], v[238:241], v[16:19]
	v_mfma_f32_16x16x32_bf16 v[4:7], v[148:151], v[246:249], v[4:7]
	s_barrier
; #define PG8_STAGE(bufoff, gbase, voff) do { _Pragma("unroll") for (int _i = 0; _i < 2; ++_i) \
;         __builtin_amdgcn_global_load_lds((const unsigned*)((const char*)(gbase) + (voff)[_i]), (LAS unsigned*)(lds + (bufoff) + ldsw + _i * 8192), 16, 0, 0); } while (0)
; #define PG8_LDA(dst, b, h) do { _Pragma("unroll") for (int m = 0; m < 4; ++m) _Pragma("unroll") for (int k = 0; k < 2; ++k) dst[m][k] = *(const LAS bf16x8*)(lds + PG8_SA(b, h) + aoff + m * 2048 + k * 1024); } while (0)
; #define PG8_LDB(dst, b, h) do { _Pragma("unroll") for (int n = 0; n < 2; ++n) _Pragma("unroll") for (int k = 0; k < 2; ++k) dst[n][k] = *(const LAS bf16x8*)(lds + PG8_SB(b, h) + boff + n * 2048 + k * 1024); } while (0)
; #define PG8_MMA(ai, bj, At, Bt) do { __builtin_amdgcn_s_setprio(1); _Pragma("unroll") for (int m = 0; m < 4; ++m) _Pragma("unroll") for (int n = 0; n < 2; ++n) _Pragma("unroll") for (int k = 0; k < 2; ++k) \
;         acc[ai][bj][m][n] = __builtin_amdgcn_mfma_f32_16x16x32_bf16(Bt[n][k], At[m][k], acc[ai][bj][m][n], 0, 0, 0); __builtin_amdgcn_s_setprio(0); } while (0)
; #define PG8_WAIT_V(n) asm volatile("s_waitcnt vmcnt(" #n ")" ::: "memory")
; #define PG8_WAIT_L(n) asm volatile("s_waitcnt lgkmcnt(" #n ")" ::: "memory")
; #define PG8_BAR __builtin_amdgcn_s_barrier()
; #define PG8_SCHED __builtin_amdgcn_sched_barrier(0)
; template <class Epi, bool KREV = false>
; __device__ __forceinline__ void gemm_phase(LAS unsigned char* lds, const Gemm g, const StaticOrder& S, const Epi& E, int wave_s) {
;     ...
;             PG8_LDB(B0, 1, 0); PG8_LDB(B1, 1, 1); PG8_SCHED; PG8_LDA(At, 1, 0); PG8_STAGE(PG8_SA(0, 1), a2 + hstep, voffA);
;             PG8_WAIT_V(8); PG8_WAIT_L(0); PG8_BAR; PG8_MMA(0, 0, At, B0); PG8_MMA(0, 1, At, B1); PG8_BAR; PG8_SCHED;
;             PG8_LDA(At, 1, 1); PG8_STAGE(PG8_SB(1, 0), b3, voffB); PG8_STAGE(PG8_SB(1, 1), b3 + bh, voffB); PG8_STAGE(PG8_SA(1, 0), a3, voffA);
;             PG8_WAIT_V(8); PG8_WAIT_L(0); PG8_BAR; PG8_MMA(1, 0, At, B0); PG8_MMA(1, 1, At, B1); PG8_BAR; PG8_SCHED;
	v_mfma_f32_16x16x32_bf16 v[0:3], v[202:205], v[246:249], v[0:3]
	s_setprio 0
	v_add_u32_e32 v140, 0x18000, v199
	v_add_u32_e32 v202, 0x1c000, v199
	ds_read_b128 v[112:115], v140
	ds_read_b128 v[124:127], v140 offset:1024
	ds_read_b128 v[136:139], v140 offset:2048
	ds_read_b128 v[140:143], v140 offset:3072
	ds_read_b128 v[144:147], v202
	ds_read_b128 v[148:151], v202 offset:1024
	ds_read_b128 v[194:197], v202 offset:2048
	ds_read_b128 v[202:205], v202 offset:3072
	ds_read_b128 v[218:221], v201 offset:32768
	ds_read_b128 v[222:225], v201 offset:33792
	ds_read_b128 v[226:229], v201 offset:34816
	ds_read_b128 v[230:233], v201 offset:35840
	ds_read_b128 v[234:237], v201 offset:36864
	ds_read_b128 v[238:241], v201 offset:37888
	ds_read_b128 v[242:245], v201 offset:38912
	ds_read_b128 v[246:249], v201 offset:39936
	s_add_i32 s27, 0, 0x18000
	s_add_i32 s45, 0, 0x1c000
	s_add_u32 s30, s30, 0x80000
	s_addc_u32 s31, s31, 0
	s_mov_b32 m0, s36
	s_nop 0
	global_load_lds_dwordx4 v156, s[30:31]
	s_mov_b32 m0, s37
	s_nop 0
	global_load_lds_dwordx4 v154, s[30:31]
	s_waitcnt vmcnt(8)
	s_waitcnt lgkmcnt(0)
	s_barrier
	s_setprio 1
	s_waitcnt lgkmcnt(0)
	v_mfma_f32_16x16x32_bf16 v[132:135], v[112:115], v[218:221], v[132:135]
	v_mfma_f32_16x16x32_bf16 v[120:123], v[136:139], v[218:221], v[120:123]
	v_mfma_f32_16x16x32_bf16 v[108:111], v[112:115], v[226:229], v[108:111]
	v_mfma_f32_16x16x32_bf16 v[104:107], v[136:139], v[226:229], v[104:107]
	v_mfma_f32_16x16x32_bf16 v[92:95], v[112:115], v[234:237], v[92:95]
	v_mfma_f32_16x16x32_bf16 v[88:91], v[136:139], v[234:237], v[88:91]
	v_mfma_f32_16x16x32_bf16 v[76:79], v[112:115], v[242:245], v[76:79]
	v_mfma_f32_16x16x32_bf16 v[72:75], v[136:139], v[242:245], v[72:75]
	v_mfma_f32_16x16x32_bf16 v[132:135], v[124:127], v[222:225], v[132:135]
	v_mfma_f32_16x16x32_bf16 v[120:123], v[140:143], v[222:225], v[120:123]
	v_mfma_f32_16x16x32_bf16 v[108:111], v[124:127], v[230:233], v[108:111]
	v_mfma_f32_16x16x32_bf16 v[104:107], v[140:143], v[230:233], v[104:107]
	v_mfma_f32_16x16x32_bf16 v[92:95], v[124:127], v[238:241], v[92:95]
	v_mfma_f32_16x16x32_bf16 v[88:91], v[140:143], v[238:241], v[88:91]
	v_mfma_f32_16x16x32_bf16 v[76:79], v[124:127], v[246:249], v[76:79]
	v_mfma_f32_16x16x32_bf16 v[72:75], v[140:143], v[246:249], v[72:75]
	s_setprio 0
	s_setprio 1
	v_mfma_f32_16x16x32_bf16 v[128:131], v[144:147], v[218:221], v[128:131]
	v_mfma_f32_16x16x32_bf16 v[116:119], v[194:197], v[218:221], v[116:119]
	v_mfma_f32_16x16x32_bf16 v[100:103], v[144:147], v[226:229], v[100:103]
	v_mfma_f32_16x16x32_bf16 v[96:99], v[194:197], v[226:229], v[96:99]
	v_mfma_f32_16x16x32_bf16 v[84:87], v[144:147], v[234:237], v[84:87]
	v_mfma_f32_16x16x32_bf16 v[80:83], v[194:197], v[234:237], v[80:83]
	v_mfma_f32_16x16x32_bf16 v[68:71], v[144:147], v[242:245], v[68:71]
	v_mfma_f32_16x16x32_bf16 v[64:67], v[194:197], v[242:245], v[64:67]
	v_mfma_f32_16x16x32_bf16 v[128:131], v[148:151], v[222:225], v[128:131]
	v_mfma_f32_16x16x32_bf16 v[116:119], v[202:205], v[222:225], v[116:119]
	v_mfma_f32_16x16x32_bf16 v[100:103], v[148:151], v[230:233], v[100:103]
	v_mfma_f32_16x16x32_bf16 v[96:99], v[202:205], v[230:233], v[96:99]
	v_mfma_f32_16x16x32_bf16 v[84:87], v[148:151], v[238:241], v[84:87]
	v_mfma_f32_16x16x32_bf16 v[80:83], v[202:205], v[238:241], v[80:83]
	v_mfma_f32_16x16x32_bf16 v[68:71], v[148:151], v[246:249], v[68:71]
	s_barrier
	v_mfma_f32_16x16x32_bf16 v[64:67], v[202:205], v[246:249], v[64:67]
	s_setprio 0
	ds_read_b128 v[218:221], v201 offset:49152
	ds_read_b128 v[222:225], v201 offset:50176
	ds_read_b128 v[226:229], v201 offset:51200
	ds_read_b128 v[230:233], v201 offset:52224
	ds_read_b128 v[234:237], v201 offset:53248
	ds_read_b128 v[238:241], v201 offset:54272
	ds_read_b128 v[242:245], v201 offset:55296
	ds_read_b128 v[246:249], v201 offset:56320
	s_add_i32 s27, s27, s1
	s_mov_b32 m0, s27
	s_nop 0
	global_load_lds_dwordx4 v176, s[98:99]
	s_add_i32 m0, s27, 0x2000
	s_add_u32 s28, s28, 0x7ff80
	s_addc_u32 s29, s29, 0
	s_add_i32 s27, s45, s1
	global_load_lds_dwordx4 v152, s[98:99]
	s_mov_b32 m0, s27
	s_nop 0
	global_load_lds_dwordx4 v176, s[28:29]
	s_add_i32 m0, s27, 0x2000
	s_nop 0
	global_load_lds_dwordx4 v152, s[28:29]
	s_mov_b32 m0, s39
	s_nop 0
	global_load_lds_dwordx4 v156, s[100:101]
	s_mov_b32 m0, s40
	s_nop 0
	global_load_lds_dwordx4 v154, s[100:101]
	s_waitcnt vmcnt(8)
	s_waitcnt lgkmcnt(0)
	s_barrier
	s_setprio 1
	s_waitcnt lgkmcnt(0)
	v_mfma_f32_16x16x32_bf16 v[60:63], v[112:115], v[218:221], v[60:63]
	v_mfma_f32_16x16x32_bf16 v[56:59], v[136:139], v[218:221], v[56:59]
	v_mfma_f32_16x16x32_bf16 v[44:47], v[112:115], v[226:229], v[44:47]
	v_mfma_f32_16x16x32_bf16 v[40:43], v[136:139], v[226:229], v[40:43]
	v_mfma_f32_16x16x32_bf16 v[28:31], v[112:115], v[234:237], v[28:31]
	v_mfma_f32_16x16x32_bf16 v[24:27], v[136:139], v[234:237], v[24:27]
	v_mfma_f32_16x16x32_bf16 v[12:15], v[112:115], v[242:245], v[12:15]
	v_mfma_f32_16x16x32_bf16 v[8:11], v[136:139], v[242:245], v[8:11]
	v_mfma_f32_16x16x32_bf16 v[60:63], v[124:127], v[222:225], v[60:63]
	v_mfma_f32_16x16x32_bf16 v[56:59], v[140:143], v[222:225], v[56:59]
	v_mfma_f32_16x16x32_bf16 v[44:47], v[124:127], v[230:233], v[44:47]
	v_mfma_f32_16x16x32_bf16 v[40:43], v[140:143], v[230:233], v[40:43]
	v_mfma_f32_16x16x32_bf16 v[28:31], v[124:127], v[238:241], v[28:31]
	v_mfma_f32_16x16x32_bf16 v[24:27], v[140:143], v[238:241], v[24:27]
	v_mfma_f32_16x16x32_bf16 v[12:15], v[124:127], v[246:249], v[12:15]
	v_mfma_f32_16x16x32_bf16 v[8:11], v[140:143], v[246:249], v[8:11]
	s_setprio 0
	s_setprio 1
	v_mfma_f32_16x16x32_bf16 v[52:55], v[144:147], v[218:221], v[52:55]
	v_mfma_f32_16x16x32_bf16 v[48:51], v[194:197], v[218:221], v[48:51]
	v_mfma_f32_16x16x32_bf16 v[36:39], v[144:147], v[226:229], v[36:39]
	v_mfma_f32_16x16x32_bf16 v[32:35], v[194:197], v[226:229], v[32:35]
	v_mfma_f32_16x16x32_bf16 v[20:23], v[144:147], v[234:237], v[20:23]
	v_mfma_f32_16x16x32_bf16 v[16:19], v[194:197], v[234:237], v[16:19]
	v_mfma_f32_16x16x32_bf16 v[4:7], v[144:147], v[242:245], v[4:7]
	v_mfma_f32_16x16x32_bf16 v[0:3], v[194:197], v[242:245], v[0:3]
	v_mfma_f32_16x16x32_bf16 v[52:55], v[148:151], v[222:225], v[52:55]
	v_mfma_f32_16x16x32_bf16 v[48:51], v[202:205], v[222:225], v[48:51]
	v_mfma_f32_16x16x32_bf16 v[36:39], v[148:151], v[230:233], v[36:39]
	v_mfma_f32_16x16x32_bf16 v[32:35], v[202:205], v[230:233], v[32:35]
	s_cmp_gt_u32 s9, 29
	s_mov_b32 s9, s26
	v_mfma_f32_16x16x32_bf16 v[20:23], v[148:151], v[238:241], v[20:23]
	v_mfma_f32_16x16x32_bf16 v[16:19], v[202:205], v[238:241], v[16:19]
	v_mfma_f32_16x16x32_bf16 v[4:7], v[148:151], v[246:249], v[4:7]
	s_barrier
	v_mfma_f32_16x16x32_bf16 v[0:3], v[202:205], v[246:249], v[0:3]
	s_setprio 0
	s_cbranch_scc1 .LBB0_645

; #define PG8_STAGE(bufoff, gbase, voff) do { _Pragma("unroll") for (int _i = 0; _i < 2; ++_i) \
;         __builtin_amdgcn_global_load_lds((const unsigned*)((const char*)(gbase) + (voff)[_i]), (LAS unsigned*)(lds + (bufoff) + ldsw + _i * 8192), 16, 0, 0); } while (0)
; #define PG8_LDA(dst, b, h) do { _Pragma("unroll") for (int m = 0; m < 4; ++m) _Pragma("unroll") for (int k = 0; k < 2; ++k) dst[m][k] = *(const LAS bf16x8*)(lds + PG8_SA(b, h) + aoff + m * 2048 + k * 1024); } while (0)
; #define PG8_LDB(dst, b, h) do { _Pragma("unroll") for (int n = 0; n < 2; ++n) _Pragma("unroll") for (int k = 0; k < 2; ++k) dst[n][k] = *(const LAS bf16x8*)(lds + PG8_SB(b, h) + boff + n * 2048 + k * 1024); } while (0)
; #define PG8_MMA(ai, bj, At, Bt) do { __builtin_amdgcn_s_setprio(1); _Pragma("unroll") for (int m = 0; m < 4; ++m) _Pragma("unroll") for (int n = 0; n < 2; ++n) _Pragma("unroll") for (int k = 0; k < 2; ++k) \
;         acc[ai][bj][m][n] = __builtin_amdgcn_mfma_f32_16x16x32_bf16(Bt[n][k], At[m][k], acc[ai][bj][m][n], 0, 0, 0); __builtin_amdgcn_s_setprio(0); } while (0)
; #define PG8_WAIT_V(n) asm volatile("s_waitcnt vmcnt(" #n ")" ::: "memory")
; #define PG8_WAIT_L(n) asm volatile("s_waitcnt lgkmcnt(" #n ")" ::: "memory")
; #define PG8_BAR __builtin_amdgcn_s_barrier()
; #define PG8_SCHED __builtin_amdgcn_sched_barrier(0)
; template <class Epi, bool KREV = false>
; __device__ __forceinline__ void gemm_phase(LAS unsigned char* lds, const Gemm g, const StaticOrder& S, const Epi& E, int wave_s) {
;     ...
;             const bool last = (t == nt - 2);
;             const char* a1 = cA + (size_t)(t + 1) * kstep;
;             const char* a2 = last ? nA : cA + (size_t)(t + 2) * kstep; const char* b2 = last ? nB : cB + (size_t)(t + 2) * kstep;
;             const char* a3 = a2 + kstep; const char* b3 = b2 + kstep;
;             PG8_LDB(B0, 0, 0); PG8_LDB(B1, 0, 1); PG8_SCHED; PG8_LDA(At, 0, 0); PG8_STAGE(PG8_SA(1, 1), a1 + hstep, voffA);
;             PG8_WAIT_V(8); PG8_WAIT_L(0); PG8_BAR; PG8_MMA(0, 0, At, B0); PG8_MMA(0, 1, At, B1); PG8_BAR; PG8_SCHED;
;             PG8_LDA(At, 0, 1); PG8_STAGE(PG8_SB(0, 0), b2, voffB); PG8_STAGE(PG8_SB(0, 1), b2 + bh, voffB); PG8_STAGE(PG8_SA(0, 0), a2, voffA);
.LBB0_836:
	v_add_u32_e32 v154, 0x10000, v135
	v_add_u32_e32 v170, 0x14000, v135
	ds_read_b128 v[142:145], v154
	ds_read_b128 v[146:149], v154 offset:1024
	ds_read_b128 v[150:153], v154 offset:2048
	ds_read_b128 v[154:157], v154 offset:3072
	ds_read_b128 v[158:161], v170
	ds_read_b128 v[162:165], v170 offset:1024
	ds_read_b128 v[166:169], v170 offset:2048
	ds_read_b128 v[170:173], v170 offset:3072
	ds_read_b128 v[178:181], v194
	ds_read_b128 v[182:185], v194 offset:1024
	ds_read_b128 v[186:189], v194 offset:2048
	ds_read_b128 v[196:199], v194 offset:3072
	ds_read_b128 v[200:203], v194 offset:4096
	ds_read_b128 v[204:207], v194 offset:5120
	ds_read_b128 v[218:221], v194 offset:6144
	ds_read_b128 v[222:225], v194 offset:7168
	s_add_u32 s56, s54, 0xfff80080
	s_addc_u32 s57, s55, -1
	s_add_i32 s84, 0, 0x10000
	s_cmp_eq_u32 s83, 28
	s_cselect_b32 s59, s73, s57
	s_cselect_b32 s58, s74, s56
	s_cselect_b32 s57, s75, s82
	s_cselect_b32 s56, s77, s80
	s_add_i32 s86, 0, 0x14000
	s_add_i32 m0, s19, 0xc000
	s_nop 0
	global_load_lds_dwordx4 v138, s[54:55]
	s_add_i32 m0, s19, 0xe000
	s_nop 0
	global_load_lds_dwordx4 v140, s[54:55]
	s_waitcnt vmcnt(8)
	s_waitcnt lgkmcnt(0)
	s_barrier
	s_setprio 1
	s_waitcnt lgkmcnt(0)
	v_mfma_f32_16x16x32_bf16 v[124:127], v[142:145], v[178:181], v[124:127]
	v_mfma_f32_16x16x32_bf16 v[120:123], v[150:153], v[178:181], v[120:123]
	v_mfma_f32_16x16x32_bf16 v[68:71], v[142:145], v[186:189], v[68:71]
	v_mfma_f32_16x16x32_bf16 v[64:67], v[150:153], v[186:189], v[64:67]
	v_mfma_f32_16x16x32_bf16 v[60:63], v[142:145], v[200:203], v[60:63]
	v_mfma_f32_16x16x32_bf16 v[20:23], v[150:153], v[200:203], v[20:23]
	v_mfma_f32_16x16x32_bf16 v[108:111], v[142:145], v[218:221], v[108:111]
	v_mfma_f32_16x16x32_bf16 v[104:107], v[150:153], v[218:221], v[104:107]
	v_mfma_f32_16x16x32_bf16 v[124:127], v[146:149], v[182:185], v[124:127]
	v_mfma_f32_16x16x32_bf16 v[120:123], v[154:157], v[182:185], v[120:123]
	v_mfma_f32_16x16x32_bf16 v[68:71], v[146:149], v[196:199], v[68:71]
	v_mfma_f32_16x16x32_bf16 v[64:67], v[154:157], v[196:199], v[64:67]
	v_mfma_f32_16x16x32_bf16 v[60:63], v[146:149], v[204:207], v[60:63]
	v_mfma_f32_16x16x32_bf16 v[20:23], v[154:157], v[204:207], v[20:23]
	v_mfma_f32_16x16x32_bf16 v[108:111], v[146:149], v[222:225], v[108:111]
	v_mfma_f32_16x16x32_bf16 v[104:107], v[154:157], v[222:225], v[104:107]
	s_setprio 0
	s_setprio 1
	v_mfma_f32_16x16x32_bf16 v[116:119], v[158:161], v[178:181], v[116:119]
	v_mfma_f32_16x16x32_bf16 v[112:115], v[166:169], v[178:181], v[112:115]
	v_mfma_f32_16x16x32_bf16 v[52:55], v[158:161], v[186:189], v[52:55]
	v_mfma_f32_16x16x32_bf16 v[48:51], v[166:169], v[186:189], v[48:51]
	v_mfma_f32_16x16x32_bf16 v[44:47], v[158:161], v[200:203], v[44:47]
	v_mfma_f32_16x16x32_bf16 v[16:19], v[166:169], v[200:203], v[16:19]
	v_mfma_f32_16x16x32_bf16 v[100:103], v[158:161], v[218:221], v[100:103]
	v_mfma_f32_16x16x32_bf16 v[96:99], v[166:169], v[218:221], v[96:99]
	v_mfma_f32_16x16x32_bf16 v[116:119], v[162:165], v[182:185], v[116:119]
	v_mfma_f32_16x16x32_bf16 v[112:115], v[170:173], v[182:185], v[112:115]
	v_mfma_f32_16x16x32_bf16 v[52:55], v[162:165], v[196:199], v[52:55]
	v_mfma_f32_16x16x32_bf16 v[48:51], v[170:173], v[196:199], v[48:51]
	v_mfma_f32_16x16x32_bf16 v[44:47], v[162:165], v[204:207], v[44:47]
	v_mfma_f32_16x16x32_bf16 v[16:19], v[170:173], v[204:207], v[16:19]
	v_mfma_f32_16x16x32_bf16 v[100:103], v[162:165], v[222:225], v[100:103]
	s_barrier
	v_mfma_f32_16x16x32_bf16 v[96:99], v[170:173], v[222:225], v[96:99]
	s_setprio 0
	ds_read_b128 v[178:181], v194 offset:16384
	ds_read_b128 v[182:185], v194 offset:17408
	ds_read_b128 v[186:189], v194 offset:18432
	ds_read_b128 v[196:199], v194 offset:19456
	ds_read_b128 v[200:203], v194 offset:20480
	ds_read_b128 v[204:207], v194 offset:21504
	ds_read_b128 v[218:221], v194 offset:22528
	ds_read_b128 v[222:225], v194 offset:23552
	s_add_u32 s98, s56, s2
	s_addc_u32 s99, s57, s3
	s_add_u32 s100, s58, s2
	s_addc_u32 s101, s59, s3
	s_add_i32 s84, s84, s66
	s_mov_b32 m0, s84
	s_nop 0
	global_load_lds_dwordx4 v176, s[56:57]
	s_add_i32 m0, s84, 0x2000
	s_add_u32 s84, s56, 0x1600000
	s_addc_u32 s85, s57, 0
	s_add_i32 s86, s86, s66
	global_load_lds_dwordx4 v132, s[56:57]
	s_mov_b32 m0, s86
	s_nop 0
	global_load_lds_dwordx4 v176, s[84:85]
	s_add_i32 m0, s86, 0x2000
	s_nop 0
	global_load_lds_dwordx4 v132, s[84:85]
	s_mov_b32 m0, s19
	s_nop 0
	global_load_lds_dwordx4 v128, s[58:59]
	s_mov_b32 m0, s21
	s_nop 0
	global_load_lds_dwordx4 v130, s[58:59]
	s_waitcnt vmcnt(8)
	s_waitcnt lgkmcnt(0)
	s_barrier
; #define PG8_STAGE(bufoff, gbase, voff) do { _Pragma("unroll") for (int _i = 0; _i < 2; ++_i) \
;         __builtin_amdgcn_global_load_lds((const unsigned*)((const char*)(gbase) + (voff)[_i]), (LAS unsigned*)(lds + (bufoff) + ldsw + _i * 8192), 16, 0, 0); } while (0)
; #define PG8_LDA(dst, b, h) do { _Pragma("unroll") for (int m = 0; m < 4; ++m) _Pragma("unroll") for (int k = 0; k < 2; ++k) dst[m][k] = *(const LAS bf16x8*)(lds + PG8_SA(b, h) + aoff + m * 2048 + k * 1024); } while (0)
; #define PG8_LDB(dst, b, h) do { _Pragma("unroll") for (int n = 0; n < 2; ++n) _Pragma("unroll") for (int k = 0; k < 2; ++k) dst[n][k] = *(const LAS bf16x8*)(lds + PG8_SB(b, h) + boff + n * 2048 + k * 1024); } while (0)
; #define PG8_MMA(ai, bj, At, Bt) do { __builtin_amdgcn_s_setprio(1); _Pragma("unroll") for (int m = 0; m < 4; ++m) _Pragma("unroll") for (int n = 0; n < 2; ++n) _Pragma("unroll") for (int k = 0; k < 2; ++k) \
;         acc[ai][bj][m][n] = __builtin_amdgcn_mfma_f32_16x16x32_bf16(Bt[n][k], At[m][k], acc[ai][bj][m][n], 0, 0, 0); __builtin_amdgcn_s_setprio(0); } while (0)
; #define PG8_WAIT_V(n) asm volatile("s_waitcnt vmcnt(" #n ")" ::: "memory")
; #define PG8_WAIT_L(n) asm volatile("s_waitcnt lgkmcnt(" #n ")" ::: "memory")
; #define PG8_BAR __builtin_amdgcn_s_barrier()
; #define PG8_SCHED __builtin_amdgcn_sched_barrier(0)
; template <class Epi, bool KREV = false>
; __device__ __forceinline__ void gemm_phase(LAS unsigned char* lds, const Gemm g, const StaticOrder& S, const Epi& E, int wave_s) {
;     ...
;             PG8_WAIT_V(8); PG8_WAIT_L(0); PG8_BAR; PG8_MMA(1, 0, At, B0); PG8_MMA(1, 1, At, B1); PG8_BAR; PG8_SCHED;
;             PG8_LDB(B0, 1, 0); PG8_LDB(B1, 1, 1); PG8_SCHED; PG8_LDA(At, 1, 0); PG8_STAGE(PG8_SA(0, 1), a2 + hstep, voffA);
;             PG8_WAIT_V(8); PG8_WAIT_L(0); PG8_BAR; PG8_MMA(0, 0, At, B0); PG8_MMA(0, 1, At, B1); PG8_BAR; PG8_SCHED;
	s_setprio 1
	s_waitcnt lgkmcnt(0)
	v_mfma_f32_16x16x32_bf16 v[92:95], v[142:145], v[178:181], v[92:95]
	v_mfma_f32_16x16x32_bf16 v[88:91], v[150:153], v[178:181], v[88:91]
	v_mfma_f32_16x16x32_bf16 v[36:39], v[142:145], v[186:189], v[36:39]
	v_mfma_f32_16x16x32_bf16 v[12:15], v[150:153], v[186:189], v[12:15]
	v_mfma_f32_16x16x32_bf16 v[32:35], v[142:145], v[200:203], v[32:35]
	v_mfma_f32_16x16x32_bf16 v[4:7], v[150:153], v[200:203], v[4:7]
	v_mfma_f32_16x16x32_bf16 v[76:79], v[142:145], v[218:221], v[76:79]
	v_mfma_f32_16x16x32_bf16 v[56:59], v[150:153], v[218:221], v[56:59]
	v_mfma_f32_16x16x32_bf16 v[92:95], v[146:149], v[182:185], v[92:95]
	v_mfma_f32_16x16x32_bf16 v[88:91], v[154:157], v[182:185], v[88:91]
	v_mfma_f32_16x16x32_bf16 v[36:39], v[146:149], v[196:199], v[36:39]
	v_mfma_f32_16x16x32_bf16 v[12:15], v[154:157], v[196:199], v[12:15]
	v_mfma_f32_16x16x32_bf16 v[32:35], v[146:149], v[204:207], v[32:35]
	v_mfma_f32_16x16x32_bf16 v[4:7], v[154:157], v[204:207], v[4:7]
	v_mfma_f32_16x16x32_bf16 v[76:79], v[146:149], v[222:225], v[76:79]
	v_mfma_f32_16x16x32_bf16 v[56:59], v[154:157], v[222:225], v[56:59]
	s_setprio 0
	s_setprio 1
	v_mfma_f32_16x16x32_bf16 v[84:87], v[158:161], v[178:181], v[84:87]
	v_mfma_f32_16x16x32_bf16 v[80:83], v[166:169], v[178:181], v[80:83]
	v_mfma_f32_16x16x32_bf16 v[28:31], v[158:161], v[186:189], v[28:31]
	v_mfma_f32_16x16x32_bf16 v[8:11], v[166:169], v[186:189], v[8:11]
	v_mfma_f32_16x16x32_bf16 v[24:27], v[158:161], v[200:203], v[24:27]
	v_mfma_f32_16x16x32_bf16 v[0:3], v[166:169], v[200:203], v[0:3]
	v_mfma_f32_16x16x32_bf16 v[72:75], v[158:161], v[218:221], v[72:75]
	v_mfma_f32_16x16x32_bf16 v[40:43], v[166:169], v[218:221], v[40:43]
	v_mfma_f32_16x16x32_bf16 v[84:87], v[162:165], v[182:185], v[84:87]
	v_mfma_f32_16x16x32_bf16 v[80:83], v[170:173], v[182:185], v[80:83]
	v_mfma_f32_16x16x32_bf16 v[28:31], v[162:165], v[196:199], v[28:31]
	v_mfma_f32_16x16x32_bf16 v[8:11], v[170:173], v[196:199], v[8:11]
	v_mfma_f32_16x16x32_bf16 v[24:27], v[162:165], v[204:207], v[24:27]
	v_mfma_f32_16x16x32_bf16 v[0:3], v[170:173], v[204:207], v[0:3]
	v_mfma_f32_16x16x32_bf16 v[72:75], v[162:165], v[222:225], v[72:75]
	s_barrier
	v_mfma_f32_16x16x32_bf16 v[40:43], v[170:173], v[222:225], v[40:43]
	s_setprio 0
	v_add_u32_e32 v154, 0x18000, v135
	v_add_u32_e32 v170, 0x1c000, v135
	ds_read_b128 v[142:145], v154
	ds_read_b128 v[146:149], v154 offset:1024
	ds_read_b128 v[150:153], v154 offset:2048
	ds_read_b128 v[154:157], v154 offset:3072
	ds_read_b128 v[158:161], v170
	ds_read_b128 v[162:165], v170 offset:1024
	ds_read_b128 v[166:169], v170 offset:2048
	ds_read_b128 v[170:173], v170 offset:3072
	ds_read_b128 v[178:181], v194 offset:32768
	ds_read_b128 v[182:185], v194 offset:33792
	ds_read_b128 v[186:189], v194 offset:34816
	ds_read_b128 v[196:199], v194 offset:35840
	ds_read_b128 v[200:203], v194 offset:36864
	ds_read_b128 v[204:207], v194 offset:37888
	ds_read_b128 v[218:221], v194 offset:38912
	ds_read_b128 v[222:225], v194 offset:39936
	s_add_i32 s84, 0, 0x18000
	s_add_i32 s85, 0, 0x1c000
	s_add_u32 s58, s58, 0x80000
	s_addc_u32 s59, s59, 0
	s_mov_b32 m0, s67
	s_nop 0
	global_load_lds_dwordx4 v128, s[58:59]
	s_mov_b32 m0, s68
	s_nop 0
	global_load_lds_dwordx4 v130, s[58:59]
	s_waitcnt vmcnt(8)
	s_waitcnt lgkmcnt(0)
	s_barrier
	s_setprio 1
	s_waitcnt lgkmcnt(0)
	v_mfma_f32_16x16x32_bf16 v[124:127], v[142:145], v[178:181], v[124:127]
	v_mfma_f32_16x16x32_bf16 v[120:123], v[150:153], v[178:181], v[120:123]
	v_mfma_f32_16x16x32_bf16 v[68:71], v[142:145], v[186:189], v[68:71]
	v_mfma_f32_16x16x32_bf16 v[64:67], v[150:153], v[186:189], v[64:67]
	v_mfma_f32_16x16x32_bf16 v[60:63], v[142:145], v[200:203], v[60:63]
	v_mfma_f32_16x16x32_bf16 v[20:23], v[150:153], v[200:203], v[20:23]
	v_mfma_f32_16x16x32_bf16 v[108:111], v[142:145], v[218:221], v[108:111]
	v_mfma_f32_16x16x32_bf16 v[104:107], v[150:153], v[218:221], v[104:107]
	v_mfma_f32_16x16x32_bf16 v[124:127], v[146:149], v[182:185], v[124:127]
	v_mfma_f32_16x16x32_bf16 v[120:123], v[154:157], v[182:185], v[120:123]
	v_mfma_f32_16x16x32_bf16 v[68:71], v[146:149], v[196:199], v[68:71]
	v_mfma_f32_16x16x32_bf16 v[64:67], v[154:157], v[196:199], v[64:67]
	v_mfma_f32_16x16x32_bf16 v[60:63], v[146:149], v[204:207], v[60:63]
	v_mfma_f32_16x16x32_bf16 v[20:23], v[154:157], v[204:207], v[20:23]
	v_mfma_f32_16x16x32_bf16 v[108:111], v[146:149], v[222:225], v[108:111]
	v_mfma_f32_16x16x32_bf16 v[104:107], v[154:157], v[222:225], v[104:107]
	s_setprio 0
	s_setprio 1
	v_mfma_f32_16x16x32_bf16 v[116:119], v[158:161], v[178:181], v[116:119]
	v_mfma_f32_16x16x32_bf16 v[112:115], v[166:169], v[178:181], v[112:115]
	v_mfma_f32_16x16x32_bf16 v[52:55], v[158:161], v[186:189], v[52:55]
	v_mfma_f32_16x16x32_bf16 v[48:51], v[166:169], v[186:189], v[48:51]
	v_mfma_f32_16x16x32_bf16 v[44:47], v[158:161], v[200:203], v[44:47]
	v_mfma_f32_16x16x32_bf16 v[16:19], v[166:169], v[200:203], v[16:19]
	v_mfma_f32_16x16x32_bf16 v[100:103], v[158:161], v[218:221], v[100:103]
	v_mfma_f32_16x16x32_bf16 v[96:99], v[166:169], v[218:221], v[96:99]
	v_mfma_f32_16x16x32_bf16 v[116:119], v[162:165], v[182:185], v[116:119]
	v_mfma_f32_16x16x32_bf16 v[112:115], v[170:173], v[182:185], v[112:115]
	v_mfma_f32_16x16x32_bf16 v[52:55], v[162:165], v[196:199], v[52:55]
	v_mfma_f32_16x16x32_bf16 v[48:51], v[170:173], v[196:199], v[48:51]
	v_mfma_f32_16x16x32_bf16 v[44:47], v[162:165], v[204:207], v[44:47]
	v_mfma_f32_16x16x32_bf16 v[16:19], v[170:173], v[204:207], v[16:19]
	v_mfma_f32_16x16x32_bf16 v[100:103], v[162:165], v[222:225], v[100:103]
	s_barrier
; #define PG8_STAGE(bufoff, gbase, voff) do { _Pragma("unroll") for (int _i = 0; _i < 2; ++_i) \
;         __builtin_amdgcn_global_load_lds((const unsigned*)((const char*)(gbase) + (voff)[_i]), (LAS unsigned*)(lds + (bufoff) + ldsw + _i * 8192), 16, 0, 0); } while (0)
; #define PG8_LDA(dst, b, h) do { _Pragma("unroll") for (int m = 0; m < 4; ++m) _Pragma("unroll") for (int k = 0; k < 2; ++k) dst[m][k] = *(const LAS bf16x8*)(lds + PG8_SA(b, h) + aoff + m * 2048 + k * 1024); } while (0)
; #define PG8_MMA(ai, bj, At, Bt) do { __builtin_amdgcn_s_setprio(1); _Pragma("unroll") for (int m = 0; m < 4; ++m) _Pragma("unroll") for (int n = 0; n < 2; ++n) _Pragma("unroll") for (int k = 0; k < 2; ++k) \
;         acc[ai][bj][m][n] = __builtin_amdgcn_mfma_f32_16x16x32_bf16(Bt[n][k], At[m][k], acc[ai][bj][m][n], 0, 0, 0); __builtin_amdgcn_s_setprio(0); } while (0)
; #define PG8_WAIT_V(n) asm volatile("s_waitcnt vmcnt(" #n ")" ::: "memory")
; #define PG8_WAIT_L(n) asm volatile("s_waitcnt lgkmcnt(" #n ")" ::: "memory")
; #define PG8_BAR __builtin_amdgcn_s_barrier()
; #define PG8_SCHED __builtin_amdgcn_sched_barrier(0)
; template <class Epi, bool KREV = false>
; __device__ __forceinline__ void gemm_phase(LAS unsigned char* lds, const Gemm g, const StaticOrder& S, const Epi& E, int wave_s) {
;     ...
;             PG8_LDA(At, 1, 1); PG8_STAGE(PG8_SB(1, 0), b3, voffB); PG8_STAGE(PG8_SB(1, 1), b3 + bh, voffB); PG8_STAGE(PG8_SA(1, 0), a3, voffA);
;             PG8_WAIT_V(8); PG8_WAIT_L(0); PG8_BAR; PG8_MMA(1, 0, At, B0); PG8_MMA(1, 1, At, B1); PG8_BAR; PG8_SCHED;
	v_mfma_f32_16x16x32_bf16 v[96:99], v[170:173], v[222:225], v[96:99]
	s_setprio 0
	ds_read_b128 v[178:181], v194 offset:49152
	ds_read_b128 v[182:185], v194 offset:50176
	ds_read_b128 v[186:189], v194 offset:51200
	ds_read_b128 v[196:199], v194 offset:52224
	ds_read_b128 v[200:203], v194 offset:53248
	ds_read_b128 v[204:207], v194 offset:54272
	ds_read_b128 v[218:221], v194 offset:55296
	ds_read_b128 v[222:225], v194 offset:56320
	s_add_i32 s58, s84, s66
	s_mov_b32 m0, s58
	s_nop 0
	global_load_lds_dwordx4 v176, s[98:99]
	s_add_i32 m0, s58, 0x2000
	s_add_u32 s56, s56, 0x1600080
	s_addc_u32 s57, s57, 0
	s_add_i32 s58, s85, s66
	global_load_lds_dwordx4 v132, s[98:99]
	s_mov_b32 m0, s58
	s_nop 0
	global_load_lds_dwordx4 v176, s[56:57]
	s_add_i32 m0, s58, 0x2000
	s_nop 0
	global_load_lds_dwordx4 v132, s[56:57]
	s_mov_b32 m0, s70
	s_nop 0
	global_load_lds_dwordx4 v128, s[100:101]
	s_mov_b32 m0, s71
	s_nop 0
	global_load_lds_dwordx4 v130, s[100:101]
	s_waitcnt vmcnt(8)
	s_waitcnt lgkmcnt(0)
	s_barrier
	s_setprio 1
	s_waitcnt lgkmcnt(0)
	v_mfma_f32_16x16x32_bf16 v[92:95], v[142:145], v[178:181], v[92:95]
	v_mfma_f32_16x16x32_bf16 v[88:91], v[150:153], v[178:181], v[88:91]
	v_mfma_f32_16x16x32_bf16 v[36:39], v[142:145], v[186:189], v[36:39]
	v_mfma_f32_16x16x32_bf16 v[12:15], v[150:153], v[186:189], v[12:15]
	v_mfma_f32_16x16x32_bf16 v[32:35], v[142:145], v[200:203], v[32:35]
	v_mfma_f32_16x16x32_bf16 v[4:7], v[150:153], v[200:203], v[4:7]
	v_mfma_f32_16x16x32_bf16 v[76:79], v[142:145], v[218:221], v[76:79]
	v_mfma_f32_16x16x32_bf16 v[56:59], v[150:153], v[218:221], v[56:59]
	v_mfma_f32_16x16x32_bf16 v[92:95], v[146:149], v[182:185], v[92:95]
	v_mfma_f32_16x16x32_bf16 v[88:91], v[154:157], v[182:185], v[88:91]
	v_mfma_f32_16x16x32_bf16 v[36:39], v[146:149], v[196:199], v[36:39]
	v_mfma_f32_16x16x32_bf16 v[12:15], v[154:157], v[196:199], v[12:15]
	v_mfma_f32_16x16x32_bf16 v[32:35], v[146:149], v[204:207], v[32:35]
	v_mfma_f32_16x16x32_bf16 v[4:7], v[154:157], v[204:207], v[4:7]
	v_mfma_f32_16x16x32_bf16 v[76:79], v[146:149], v[222:225], v[76:79]
	v_mfma_f32_16x16x32_bf16 v[56:59], v[154:157], v[222:225], v[56:59]
	s_setprio 0
	s_setprio 1
	v_mfma_f32_16x16x32_bf16 v[84:87], v[158:161], v[178:181], v[84:87]
	v_mfma_f32_16x16x32_bf16 v[80:83], v[166:169], v[178:181], v[80:83]
	v_mfma_f32_16x16x32_bf16 v[28:31], v[158:161], v[186:189], v[28:31]
	v_mfma_f32_16x16x32_bf16 v[8:11], v[166:169], v[186:189], v[8:11]
	v_mfma_f32_16x16x32_bf16 v[24:27], v[158:161], v[200:203], v[24:27]
	v_mfma_f32_16x16x32_bf16 v[0:3], v[166:169], v[200:203], v[0:3]
	v_mfma_f32_16x16x32_bf16 v[72:75], v[158:161], v[218:221], v[72:75]
	v_mfma_f32_16x16x32_bf16 v[40:43], v[166:169], v[218:221], v[40:43]
	v_mfma_f32_16x16x32_bf16 v[84:87], v[162:165], v[182:185], v[84:87]
	v_mfma_f32_16x16x32_bf16 v[80:83], v[170:173], v[182:185], v[80:83]
	v_mfma_f32_16x16x32_bf16 v[28:31], v[162:165], v[196:199], v[28:31]
	v_mfma_f32_16x16x32_bf16 v[8:11], v[170:173], v[196:199], v[8:11]
	s_add_i32 s83, s83, 2
	s_add_u32 s54, s54, 0x100
	s_addc_u32 s55, s55, 0
	v_mfma_f32_16x16x32_bf16 v[24:27], v[162:165], v[204:207], v[24:27]
	s_add_u32 s80, s80, 0x100
	s_addc_u32 s82, s82, 0
	v_mfma_f32_16x16x32_bf16 v[0:3], v[170:173], v[204:207], v[0:3]
	s_cmp_gt_u32 s83, 29
	v_mfma_f32_16x16x32_bf16 v[72:75], v[162:165], v[222:225], v[72:75]
	s_barrier
	v_mfma_f32_16x16x32_bf16 v[40:43], v[170:173], v[222:225], v[40:43]
	s_setprio 0
	s_cbranch_scc0 .LBB0_836
	s_and_b64 vcc, exec, s[38:39]
	s_cbranch_vccz .LBB0_839
	s_barrier

; #define PG8_STAGE(bufoff, gbase, voff) do { _Pragma("unroll") for (int _i = 0; _i < 2; ++_i) \
;         __builtin_amdgcn_global_load_lds((const unsigned*)((const char*)(gbase) + (voff)[_i]), (LAS unsigned*)(lds + (bufoff) + ldsw + _i * 8192), 16, 0, 0); } while (0)
; #define PG8_LDA(dst, b, h) do { _Pragma("unroll") for (int m = 0; m < 4; ++m) _Pragma("unroll") for (int k = 0; k < 2; ++k) dst[m][k] = *(const LAS bf16x8*)(lds + PG8_SA(b, h) + aoff + m * 2048 + k * 1024); } while (0)
; #define PG8_LDB(dst, b, h) do { _Pragma("unroll") for (int n = 0; n < 2; ++n) _Pragma("unroll") for (int k = 0; k < 2; ++k) dst[n][k] = *(const LAS bf16x8*)(lds + PG8_SB(b, h) + boff + n * 2048 + k * 1024); } while (0)
; #define PG8_MMA(ai, bj, At, Bt) do { __builtin_amdgcn_s_setprio(1); _Pragma("unroll") for (int m = 0; m < 4; ++m) _Pragma("unroll") for (int n = 0; n < 2; ++n) _Pragma("unroll") for (int k = 0; k < 2; ++k) \
;         acc[ai][bj][m][n] = __builtin_amdgcn_mfma_f32_16x16x32_bf16(Bt[n][k], At[m][k], acc[ai][bj][m][n], 0, 0, 0); __builtin_amdgcn_s_setprio(0); } while (0)
; #define PG8_WAIT_V(n) asm volatile("s_waitcnt vmcnt(" #n ")" ::: "memory")
; #define PG8_WAIT_L(n) asm volatile("s_waitcnt lgkmcnt(" #n ")" ::: "memory")
; #define PG8_BAR __builtin_amdgcn_s_barrier()
; #define PG8_SCHED __builtin_amdgcn_sched_barrier(0)
; template <class Epi, bool KREV = false>
; __device__ __forceinline__ void gemm_phase(LAS unsigned char* lds, const Gemm g, const StaticOrder& S, const Epi& E, int wave_s) {
;     ...
;             PG8_LDB(B0, 0, 0); PG8_LDB(B1, 0, 1); PG8_SCHED; PG8_LDA(At, 0, 0); PG8_STAGE(PG8_SA(1, 1), a1 + hstep, voffA);
;             PG8_WAIT_V(8); PG8_WAIT_L(0); PG8_BAR; PG8_MMA(0, 0, At, B0); PG8_MMA(0, 1, At, B1); PG8_BAR; PG8_SCHED;
;             PG8_LDA(At, 0, 1); PG8_STAGE(PG8_SB(0, 0), b2, voffB); PG8_STAGE(PG8_SB(0, 1), b2 + bh, voffB); PG8_STAGE(PG8_SA(0, 0), a2, voffA);
;             PG8_WAIT_V(8); PG8_WAIT_L(0); PG8_BAR; PG8_MMA(1, 0, At, B0); PG8_MMA(1, 1, At, B1); PG8_BAR; PG8_SCHED;
.LBB0_1023:
	s_or_b32 s80, s44, 1
	s_lshl_b64 s[46:47], s[80:81], 7
	s_sub_u32 s23, 0, s46
	s_subb_u32 s45, 0, s47
	s_add_i32 s48, 0, 0x10000
	s_add_i32 s49, 0, 0x14000
	s_add_u32 s46, s42, s23
	s_addc_u32 s47, s43, s45
	s_add_i32 m0, s28, 0xc000
	s_nop 0
	global_load_lds_dwordx4 v156, s[46:47]
	s_add_i32 m0, s28, 0xe000
	s_nop 0
	global_load_lds_dwordx4 v154, s[46:47]
	s_waitcnt vmcnt(8)
	s_waitcnt lgkmcnt(0)
	s_barrier
	s_setprio 1
	s_waitcnt lgkmcnt(0)
	v_mfma_f32_16x16x32_bf16 v[132:135], v[112:115], v[218:221], v[132:135]
	v_mfma_f32_16x16x32_bf16 v[120:123], v[136:139], v[218:221], v[120:123]
	v_mfma_f32_16x16x32_bf16 v[108:111], v[112:115], v[226:229], v[108:111]
	v_mfma_f32_16x16x32_bf16 v[104:107], v[136:139], v[226:229], v[104:107]
	v_mfma_f32_16x16x32_bf16 v[92:95], v[112:115], v[234:237], v[92:95]
	v_mfma_f32_16x16x32_bf16 v[88:91], v[136:139], v[234:237], v[88:91]
	v_mfma_f32_16x16x32_bf16 v[76:79], v[112:115], v[242:245], v[76:79]
	v_mfma_f32_16x16x32_bf16 v[72:75], v[136:139], v[242:245], v[72:75]
	v_mfma_f32_16x16x32_bf16 v[132:135], v[124:127], v[222:225], v[132:135]
	v_mfma_f32_16x16x32_bf16 v[120:123], v[140:143], v[222:225], v[120:123]
	v_mfma_f32_16x16x32_bf16 v[108:111], v[124:127], v[230:233], v[108:111]
	v_mfma_f32_16x16x32_bf16 v[104:107], v[140:143], v[230:233], v[104:107]
	v_mfma_f32_16x16x32_bf16 v[92:95], v[124:127], v[238:241], v[92:95]
	v_mfma_f32_16x16x32_bf16 v[88:91], v[140:143], v[238:241], v[88:91]
	v_mfma_f32_16x16x32_bf16 v[76:79], v[124:127], v[246:249], v[76:79]
	v_mfma_f32_16x16x32_bf16 v[72:75], v[140:143], v[246:249], v[72:75]
	s_setprio 0
	s_setprio 1
	v_mfma_f32_16x16x32_bf16 v[128:131], v[144:147], v[218:221], v[128:131]
	v_mfma_f32_16x16x32_bf16 v[116:119], v[194:197], v[218:221], v[116:119]
	v_mfma_f32_16x16x32_bf16 v[100:103], v[144:147], v[226:229], v[100:103]
	v_mfma_f32_16x16x32_bf16 v[96:99], v[194:197], v[226:229], v[96:99]
	v_mfma_f32_16x16x32_bf16 v[84:87], v[144:147], v[234:237], v[84:87]
	v_mfma_f32_16x16x32_bf16 v[80:83], v[194:197], v[234:237], v[80:83]
	v_mfma_f32_16x16x32_bf16 v[68:71], v[144:147], v[242:245], v[68:71]
	v_mfma_f32_16x16x32_bf16 v[64:67], v[194:197], v[242:245], v[64:67]
	v_mfma_f32_16x16x32_bf16 v[128:131], v[148:151], v[222:225], v[128:131]
	v_mfma_f32_16x16x32_bf16 v[116:119], v[202:205], v[222:225], v[116:119]
	v_mfma_f32_16x16x32_bf16 v[100:103], v[148:151], v[230:233], v[100:103]
	v_mfma_f32_16x16x32_bf16 v[96:99], v[202:205], v[230:233], v[96:99]
	v_mfma_f32_16x16x32_bf16 v[84:87], v[148:151], v[238:241], v[84:87]
	v_mfma_f32_16x16x32_bf16 v[80:83], v[202:205], v[238:241], v[80:83]
	v_mfma_f32_16x16x32_bf16 v[68:71], v[148:151], v[246:249], v[68:71]
	s_barrier
	v_mfma_f32_16x16x32_bf16 v[64:67], v[202:205], v[246:249], v[64:67]
	s_setprio 0
	ds_read_b128 v[218:221], v201 offset:16384
	ds_read_b128 v[222:225], v201 offset:17408
	ds_read_b128 v[226:229], v201 offset:18432
	ds_read_b128 v[230:233], v201 offset:19456
	ds_read_b128 v[234:237], v201 offset:20480
	ds_read_b128 v[238:241], v201 offset:21504
	ds_read_b128 v[242:245], v201 offset:22528
	ds_read_b128 v[246:249], v201 offset:23552
	s_add_u32 s98, s24, s78
	s_addc_u32 s99, s25, s79
	s_add_u32 s100, s26, s78
	s_addc_u32 s101, s27, s79
	s_add_i32 s23, s48, s1
	s_mov_b32 m0, s23
	s_nop 0
	global_load_lds_dwordx4 v176, s[24:25]
	s_add_i32 m0, s23, 0x2000
	s_add_u32 s46, s24, 0x160000
	s_addc_u32 s47, s25, 0
	s_add_i32 s23, s49, s1
	global_load_lds_dwordx4 v152, s[24:25]
	s_mov_b32 m0, s23
	s_nop 0
	global_load_lds_dwordx4 v176, s[46:47]
	s_add_i32 m0, s23, 0x2000
	s_nop 0
	global_load_lds_dwordx4 v152, s[46:47]
	s_mov_b32 m0, s28
	s_nop 0
	global_load_lds_dwordx4 v156, s[26:27]
	s_mov_b32 m0, s29
	s_nop 0
	global_load_lds_dwordx4 v154, s[26:27]
	s_waitcnt vmcnt(8)
	s_waitcnt lgkmcnt(0)
	s_barrier
	s_setprio 1
	s_waitcnt lgkmcnt(0)
	v_mfma_f32_16x16x32_bf16 v[60:63], v[112:115], v[218:221], v[60:63]
	v_mfma_f32_16x16x32_bf16 v[56:59], v[136:139], v[218:221], v[56:59]
	v_mfma_f32_16x16x32_bf16 v[44:47], v[112:115], v[226:229], v[44:47]
	v_mfma_f32_16x16x32_bf16 v[40:43], v[136:139], v[226:229], v[40:43]
	v_mfma_f32_16x16x32_bf16 v[28:31], v[112:115], v[234:237], v[28:31]
	v_mfma_f32_16x16x32_bf16 v[24:27], v[136:139], v[234:237], v[24:27]
	v_mfma_f32_16x16x32_bf16 v[12:15], v[112:115], v[242:245], v[12:15]
	v_mfma_f32_16x16x32_bf16 v[8:11], v[136:139], v[242:245], v[8:11]
	v_mfma_f32_16x16x32_bf16 v[60:63], v[124:127], v[222:225], v[60:63]
	v_mfma_f32_16x16x32_bf16 v[56:59], v[140:143], v[222:225], v[56:59]
	v_mfma_f32_16x16x32_bf16 v[44:47], v[124:127], v[230:233], v[44:47]
	v_mfma_f32_16x16x32_bf16 v[40:43], v[140:143], v[230:233], v[40:43]
	v_mfma_f32_16x16x32_bf16 v[28:31], v[124:127], v[238:241], v[28:31]
	v_mfma_f32_16x16x32_bf16 v[24:27], v[140:143], v[238:241], v[24:27]
	v_mfma_f32_16x16x32_bf16 v[12:15], v[124:127], v[246:249], v[12:15]
	v_mfma_f32_16x16x32_bf16 v[8:11], v[140:143], v[246:249], v[8:11]
	s_setprio 0
	s_setprio 1
	v_mfma_f32_16x16x32_bf16 v[52:55], v[144:147], v[218:221], v[52:55]
	v_mfma_f32_16x16x32_bf16 v[48:51], v[194:197], v[218:221], v[48:51]
	v_mfma_f32_16x16x32_bf16 v[36:39], v[144:147], v[226:229], v[36:39]
	v_mfma_f32_16x16x32_bf16 v[32:35], v[194:197], v[226:229], v[32:35]
	v_mfma_f32_16x16x32_bf16 v[20:23], v[144:147], v[234:237], v[20:23]
	v_mfma_f32_16x16x32_bf16 v[16:19], v[194:197], v[234:237], v[16:19]
	v_mfma_f32_16x16x32_bf16 v[4:7], v[144:147], v[242:245], v[4:7]
	v_mfma_f32_16x16x32_bf16 v[0:3], v[194:197], v[242:245], v[0:3]
	v_mfma_f32_16x16x32_bf16 v[52:55], v[148:151], v[222:225], v[52:55]
	v_mfma_f32_16x16x32_bf16 v[48:51], v[202:205], v[222:225], v[48:51]
	v_mfma_f32_16x16x32_bf16 v[36:39], v[148:151], v[230:233], v[36:39]
	v_mfma_f32_16x16x32_bf16 v[32:35], v[202:205], v[230:233], v[32:35]
	v_mfma_f32_16x16x32_bf16 v[20:23], v[148:151], v[238:241], v[20:23]
	v_mfma_f32_16x16x32_bf16 v[16:19], v[202:205], v[238:241], v[16:19]
	v_mfma_f32_16x16x32_bf16 v[4:7], v[148:151], v[246:249], v[4:7]
	s_barrier
; #define PG8_STAGE(bufoff, gbase, voff) do { _Pragma("unroll") for (int _i = 0; _i < 2; ++_i) \
;         __builtin_amdgcn_global_load_lds((const unsigned*)((const char*)(gbase) + (voff)[_i]), (LAS unsigned*)(lds + (bufoff) + ldsw + _i * 8192), 16, 0, 0); } while (0)
; #define PG8_LDA(dst, b, h) do { _Pragma("unroll") for (int m = 0; m < 4; ++m) _Pragma("unroll") for (int k = 0; k < 2; ++k) dst[m][k] = *(const LAS bf16x8*)(lds + PG8_SA(b, h) + aoff + m * 2048 + k * 1024); } while (0)
; #define PG8_LDB(dst, b, h) do { _Pragma("unroll") for (int n = 0; n < 2; ++n) _Pragma("unroll") for (int k = 0; k < 2; ++k) dst[n][k] = *(const LAS bf16x8*)(lds + PG8_SB(b, h) + boff + n * 2048 + k * 1024); } while (0)
; #define PG8_MMA(ai, bj, At, Bt) do { __builtin_amdgcn_s_setprio(1); _Pragma("unroll") for (int m = 0; m < 4; ++m) _Pragma("unroll") for (int n = 0; n < 2; ++n) _Pragma("unroll") for (int k = 0; k < 2; ++k) \
;         acc[ai][bj][m][n] = __builtin_amdgcn_mfma_f32_16x16x32_bf16(Bt[n][k], At[m][k], acc[ai][bj][m][n], 0, 0, 0); __builtin_amdgcn_s_setprio(0); } while (0)
; #define PG8_WAIT_V(n) asm volatile("s_waitcnt vmcnt(" #n ")" ::: "memory")
; #define PG8_WAIT_L(n) asm volatile("s_waitcnt lgkmcnt(" #n ")" ::: "memory")
; #define PG8_BAR __builtin_amdgcn_s_barrier()
; #define PG8_SCHED __builtin_amdgcn_sched_barrier(0)
; template <class Epi, bool KREV = false>
; __device__ __forceinline__ void gemm_phase(LAS unsigned char* lds, const Gemm g, const StaticOrder& S, const Epi& E, int wave_s) {
;     ...
;             PG8_LDB(B0, 1, 0); PG8_LDB(B1, 1, 1); PG8_SCHED; PG8_LDA(At, 1, 0); PG8_STAGE(PG8_SA(0, 1), a2 + hstep, voffA);
;             PG8_WAIT_V(8); PG8_WAIT_L(0); PG8_BAR; PG8_MMA(0, 0, At, B0); PG8_MMA(0, 1, At, B1); PG8_BAR; PG8_SCHED;
;             PG8_LDA(At, 1, 1); PG8_STAGE(PG8_SB(1, 0), b3, voffB); PG8_STAGE(PG8_SB(1, 1), b3 + bh, voffB); PG8_STAGE(PG8_SA(1, 0), a3, voffA);
;             PG8_WAIT_V(8); PG8_WAIT_L(0); PG8_BAR; PG8_MMA(1, 0, At, B0); PG8_MMA(1, 1, At, B1); PG8_BAR; PG8_SCHED;
	v_mfma_f32_16x16x32_bf16 v[0:3], v[202:205], v[246:249], v[0:3]
	s_setprio 0
	v_add_u32_e32 v140, 0x18000, v199
	v_add_u32_e32 v202, 0x1c000, v199
	ds_read_b128 v[112:115], v140
	ds_read_b128 v[124:127], v140 offset:1024
	ds_read_b128 v[136:139], v140 offset:2048
	ds_read_b128 v[140:143], v140 offset:3072
	ds_read_b128 v[144:147], v202
	ds_read_b128 v[148:151], v202 offset:1024
	ds_read_b128 v[194:197], v202 offset:2048
	ds_read_b128 v[202:205], v202 offset:3072
	ds_read_b128 v[218:221], v201 offset:32768
	ds_read_b128 v[222:225], v201 offset:33792
	ds_read_b128 v[226:229], v201 offset:34816
	ds_read_b128 v[230:233], v201 offset:35840
	ds_read_b128 v[234:237], v201 offset:36864
	ds_read_b128 v[238:241], v201 offset:37888
	ds_read_b128 v[242:245], v201 offset:38912
	ds_read_b128 v[246:249], v201 offset:39936
	s_add_i32 s23, 0, 0x18000
	s_add_i32 s45, 0, 0x1c000
	s_add_u32 s26, s26, 0x160000
	s_addc_u32 s27, s27, 0
	s_mov_b32 m0, s30
	s_nop 0
	global_load_lds_dwordx4 v156, s[26:27]
	s_mov_b32 m0, s34
	s_nop 0
	global_load_lds_dwordx4 v154, s[26:27]
	s_waitcnt vmcnt(8)
	s_waitcnt lgkmcnt(0)
	s_barrier
	s_setprio 1
	s_waitcnt lgkmcnt(0)
	v_mfma_f32_16x16x32_bf16 v[132:135], v[112:115], v[218:221], v[132:135]
	v_mfma_f32_16x16x32_bf16 v[120:123], v[136:139], v[218:221], v[120:123]
	v_mfma_f32_16x16x32_bf16 v[108:111], v[112:115], v[226:229], v[108:111]
	v_mfma_f32_16x16x32_bf16 v[104:107], v[136:139], v[226:229], v[104:107]
	v_mfma_f32_16x16x32_bf16 v[92:95], v[112:115], v[234:237], v[92:95]
	v_mfma_f32_16x16x32_bf16 v[88:91], v[136:139], v[234:237], v[88:91]
	v_mfma_f32_16x16x32_bf16 v[76:79], v[112:115], v[242:245], v[76:79]
	v_mfma_f32_16x16x32_bf16 v[72:75], v[136:139], v[242:245], v[72:75]
	v_mfma_f32_16x16x32_bf16 v[132:135], v[124:127], v[222:225], v[132:135]
	v_mfma_f32_16x16x32_bf16 v[120:123], v[140:143], v[222:225], v[120:123]
	v_mfma_f32_16x16x32_bf16 v[108:111], v[124:127], v[230:233], v[108:111]
	v_mfma_f32_16x16x32_bf16 v[104:107], v[140:143], v[230:233], v[104:107]
	v_mfma_f32_16x16x32_bf16 v[92:95], v[124:127], v[238:241], v[92:95]
	v_mfma_f32_16x16x32_bf16 v[88:91], v[140:143], v[238:241], v[88:91]
	v_mfma_f32_16x16x32_bf16 v[76:79], v[124:127], v[246:249], v[76:79]
	v_mfma_f32_16x16x32_bf16 v[72:75], v[140:143], v[246:249], v[72:75]
	s_setprio 0
	s_setprio 1
	v_mfma_f32_16x16x32_bf16 v[128:131], v[144:147], v[218:221], v[128:131]
	v_mfma_f32_16x16x32_bf16 v[116:119], v[194:197], v[218:221], v[116:119]
	v_mfma_f32_16x16x32_bf16 v[100:103], v[144:147], v[226:229], v[100:103]
	v_mfma_f32_16x16x32_bf16 v[96:99], v[194:197], v[226:229], v[96:99]
	v_mfma_f32_16x16x32_bf16 v[84:87], v[144:147], v[234:237], v[84:87]
	v_mfma_f32_16x16x32_bf16 v[80:83], v[194:197], v[234:237], v[80:83]
	v_mfma_f32_16x16x32_bf16 v[68:71], v[144:147], v[242:245], v[68:71]
	v_mfma_f32_16x16x32_bf16 v[64:67], v[194:197], v[242:245], v[64:67]
	v_mfma_f32_16x16x32_bf16 v[128:131], v[148:151], v[222:225], v[128:131]
	v_mfma_f32_16x16x32_bf16 v[116:119], v[202:205], v[222:225], v[116:119]
	v_mfma_f32_16x16x32_bf16 v[100:103], v[148:151], v[230:233], v[100:103]
	v_mfma_f32_16x16x32_bf16 v[96:99], v[202:205], v[230:233], v[96:99]
	v_mfma_f32_16x16x32_bf16 v[84:87], v[148:151], v[238:241], v[84:87]
	v_mfma_f32_16x16x32_bf16 v[80:83], v[202:205], v[238:241], v[80:83]
	v_mfma_f32_16x16x32_bf16 v[68:71], v[148:151], v[246:249], v[68:71]
	s_barrier
	v_mfma_f32_16x16x32_bf16 v[64:67], v[202:205], v[246:249], v[64:67]
	s_setprio 0
	ds_read_b128 v[218:221], v201 offset:49152
	ds_read_b128 v[222:225], v201 offset:50176
	ds_read_b128 v[226:229], v201 offset:51200
	ds_read_b128 v[230:233], v201 offset:52224
	ds_read_b128 v[234:237], v201 offset:53248
	ds_read_b128 v[238:241], v201 offset:54272
	ds_read_b128 v[242:245], v201 offset:55296
	ds_read_b128 v[246:249], v201 offset:56320
	s_add_i32 s23, s23, s1
	s_mov_b32 m0, s23
	s_nop 0
	global_load_lds_dwordx4 v176, s[98:99]
	s_add_i32 m0, s23, 0x2000
	s_add_u32 s24, s24, 0x15ff80
	s_addc_u32 s25, s25, 0
	s_add_i32 s23, s45, s1
	global_load_lds_dwordx4 v152, s[98:99]
	s_mov_b32 m0, s23
	s_nop 0
	global_load_lds_dwordx4 v176, s[24:25]
	s_add_i32 m0, s23, 0x2000
	s_nop 0
	global_load_lds_dwordx4 v152, s[24:25]
	s_mov_b32 m0, s36
	s_nop 0
	global_load_lds_dwordx4 v156, s[100:101]
	s_mov_b32 m0, s37
	s_nop 0
	global_load_lds_dwordx4 v154, s[100:101]
	s_waitcnt vmcnt(8)
	s_waitcnt lgkmcnt(0)
	s_barrier
	s_setprio 1
	s_waitcnt lgkmcnt(0)
	v_mfma_f32_16x16x32_bf16 v[60:63], v[112:115], v[218:221], v[60:63]
	v_mfma_f32_16x16x32_bf16 v[56:59], v[136:139], v[218:221], v[56:59]
	v_mfma_f32_16x16x32_bf16 v[44:47], v[112:115], v[226:229], v[44:47]
	v_mfma_f32_16x16x32_bf16 v[40:43], v[136:139], v[226:229], v[40:43]
	v_mfma_f32_16x16x32_bf16 v[28:31], v[112:115], v[234:237], v[28:31]
	v_mfma_f32_16x16x32_bf16 v[24:27], v[136:139], v[234:237], v[24:27]
	v_mfma_f32_16x16x32_bf16 v[12:15], v[112:115], v[242:245], v[12:15]
	v_mfma_f32_16x16x32_bf16 v[8:11], v[136:139], v[242:245], v[8:11]
	v_mfma_f32_16x16x32_bf16 v[60:63], v[124:127], v[222:225], v[60:63]
	v_mfma_f32_16x16x32_bf16 v[56:59], v[140:143], v[222:225], v[56:59]
	v_mfma_f32_16x16x32_bf16 v[44:47], v[124:127], v[230:233], v[44:47]
	v_mfma_f32_16x16x32_bf16 v[40:43], v[140:143], v[230:233], v[40:43]
	v_mfma_f32_16x16x32_bf16 v[28:31], v[124:127], v[238:241], v[28:31]
	v_mfma_f32_16x16x32_bf16 v[24:27], v[140:143], v[238:241], v[24:27]
	v_mfma_f32_16x16x32_bf16 v[12:15], v[124:127], v[246:249], v[12:15]
	v_mfma_f32_16x16x32_bf16 v[8:11], v[140:143], v[246:249], v[8:11]
	s_setprio 0
	s_setprio 1
	v_mfma_f32_16x16x32_bf16 v[52:55], v[144:147], v[218:221], v[52:55]
	v_mfma_f32_16x16x32_bf16 v[48:51], v[194:197], v[218:221], v[48:51]
	v_mfma_f32_16x16x32_bf16 v[36:39], v[144:147], v[226:229], v[36:39]
	v_mfma_f32_16x16x32_bf16 v[32:35], v[194:197], v[226:229], v[32:35]
	v_mfma_f32_16x16x32_bf16 v[20:23], v[144:147], v[234:237], v[20:23]
	v_mfma_f32_16x16x32_bf16 v[16:19], v[194:197], v[234:237], v[16:19]
	v_mfma_f32_16x16x32_bf16 v[4:7], v[144:147], v[242:245], v[4:7]
	v_mfma_f32_16x16x32_bf16 v[0:3], v[194:197], v[242:245], v[0:3]
	v_mfma_f32_16x16x32_bf16 v[52:55], v[148:151], v[222:225], v[52:55]
	v_mfma_f32_16x16x32_bf16 v[48:51], v[202:205], v[222:225], v[48:51]
	v_mfma_f32_16x16x32_bf16 v[36:39], v[148:151], v[230:233], v[36:39]
	v_mfma_f32_16x16x32_bf16 v[32:35], v[202:205], v[230:233], v[32:35]
	s_cmpk_gt_u32 s44, 0x55
	s_mov_b32 s44, s22
	v_mfma_f32_16x16x32_bf16 v[20:23], v[148:151], v[238:241], v[20:23]
	v_mfma_f32_16x16x32_bf16 v[16:19], v[202:205], v[238:241], v[16:19]
	v_mfma_f32_16x16x32_bf16 v[4:7], v[148:151], v[246:249], v[4:7]
	s_barrier
	v_mfma_f32_16x16x32_bf16 v[0:3], v[202:205], v[246:249], v[0:3]
	s_setprio 0
	s_cbranch_scc1 .LBB0_1028
